# first K-tile pair peeled: first MFMA of each accumulator takes C=0, the 128 v_mov accumulator clears per unit removed (on top of kinner_bj order)
# baseline (speedup 1.0000x reference)
.LBB0_146:
	s_ashr_i32 s25, s24, 31
	s_lshl_b64 s[26:27], s[24:25], 20
	s_add_u32 s26, s47, s26
	s_addc_u32 s27, s48, s27
	s_and_b64 s[28:29], s[38:39], exec
	s_cselect_b32 s2, s27, s41
	s_cselect_b32 s5, s26, s40
	s_ashr_i32 s23, s22, 31
	s_lshl_b64 s[28:29], s[22:23], 20
	s_add_u32 s28, s49, s28
	s_addc_u32 s29, s50, s29
	s_and_b64 s[44:45], s[38:39], exec
	s_cselect_b32 s23, s29, s43
	s_cselect_b32 s25, s28, s42
	s_add_u32 s40, s40, 0x80080
	s_addc_u32 s41, s41, 0
	s_add_u32 s31, s42, 0x100
	s_addc_u32 s62, s43, 0
	s_mov_b32 s63, -2
	s_sleep 2
	s_add_u32 s42, s40, 0xfff80080
	s_addc_u32 s43, s41, -1
	s_add_i32 s71, 0, 0x10000
	s_cmp_eq_u32 s63, 28
	s_cselect_b32 s45, s2, s43
	s_cselect_b32 s44, s5, s42
	s_cselect_b32 s43, s23, s62
	s_cselect_b32 s42, s25, s31
	s_add_i32 s73, 0, 0x14000
	s_waitcnt lgkmcnt(0)
	v_add_u32_e32 v156, s71, v169
	v_add_u32_e32 v178, s73, v169
	ds_read_b128 v[132:135], v156
	ds_read_b128 v[136:139], v156 offset:1024
	ds_read_b128 v[152:155], v156 offset:2048
	ds_read_b128 v[156:159], v156 offset:3072
	ds_read_b128 v[160:163], v178
	ds_read_b128 v[164:167], v178 offset:1024
	ds_read_b128 v[174:177], v178 offset:2048
	ds_read_b128 v[178:181], v178 offset:3072
	v_lshl_add_u64 v[202:203], s[40:41], 0, v[148:149]
	s_add_i32 m0, s53, 0xc000
	ds_read_b128 v[182:185], v171
	ds_read_b128 v[186:189], v171 offset:1024
	ds_read_b128 v[190:193], v171 offset:2048
	ds_read_b128 v[194:197], v171 offset:3072
	ds_read_b128 v[198:201], v171 offset:4096
	ds_read_b128 v[208:211], v171 offset:5120
	ds_read_b128 v[212:215], v171 offset:6144
	ds_read_b128 v[216:219], v171 offset:7168
	global_load_lds_dwordx4 v[202:203], off
	v_lshl_add_u64 v[202:203], s[40:41], 0, v[150:151]
	s_add_i32 m0, s53, 0xe000
	s_nop 0
	global_load_lds_dwordx4 v[202:203], off
	s_waitcnt vmcnt(8)
	s_waitcnt lgkmcnt(0)
	s_barrier
	s_setprio 1
	s_waitcnt lgkmcnt(0)
	v_mfma_f32_16x16x32_bf16 v[128:131], v[132:135], v[182:185], 0
	v_mfma_f32_16x16x32_bf16 v[128:131], v[136:139], v[186:189], v[128:131]
	v_mfma_f32_16x16x32_bf16 v[116:119], v[160:163], v[182:185], 0
	v_mfma_f32_16x16x32_bf16 v[116:119], v[164:167], v[186:189], v[116:119]
	v_mfma_f32_16x16x32_bf16 v[124:127], v[152:155], v[182:185], 0
	v_mfma_f32_16x16x32_bf16 v[124:127], v[156:159], v[186:189], v[124:127]
	v_mfma_f32_16x16x32_bf16 v[108:111], v[174:177], v[182:185], 0
	v_mfma_f32_16x16x32_bf16 v[108:111], v[178:181], v[186:189], v[108:111]
	v_mfma_f32_16x16x32_bf16 v[120:123], v[132:135], v[190:193], 0
	v_mfma_f32_16x16x32_bf16 v[120:123], v[136:139], v[194:197], v[120:123]
	v_mfma_f32_16x16x32_bf16 v[100:103], v[160:163], v[190:193], 0
	v_mfma_f32_16x16x32_bf16 v[100:103], v[164:167], v[194:197], v[100:103]
	v_mfma_f32_16x16x32_bf16 v[112:115], v[152:155], v[190:193], 0
	v_mfma_f32_16x16x32_bf16 v[112:115], v[156:159], v[194:197], v[112:115]
	v_mfma_f32_16x16x32_bf16 v[92:95], v[174:177], v[190:193], 0
	v_mfma_f32_16x16x32_bf16 v[92:95], v[178:181], v[194:197], v[92:95]
	v_mfma_f32_16x16x32_bf16 v[104:107], v[132:135], v[198:201], 0
	v_mfma_f32_16x16x32_bf16 v[104:107], v[136:139], v[208:211], v[104:107]
	v_mfma_f32_16x16x32_bf16 v[84:87], v[160:163], v[198:201], 0
	v_mfma_f32_16x16x32_bf16 v[84:87], v[164:167], v[208:211], v[84:87]
	v_mfma_f32_16x16x32_bf16 v[96:99], v[152:155], v[198:201], 0
	v_mfma_f32_16x16x32_bf16 v[96:99], v[156:159], v[208:211], v[96:99]
	v_mfma_f32_16x16x32_bf16 v[76:79], v[174:177], v[198:201], 0
	v_mfma_f32_16x16x32_bf16 v[76:79], v[178:181], v[208:211], v[76:79]
	v_mfma_f32_16x16x32_bf16 v[88:91], v[132:135], v[212:215], 0
	v_mfma_f32_16x16x32_bf16 v[88:91], v[136:139], v[216:219], v[88:91]
	v_mfma_f32_16x16x32_bf16 v[72:75], v[160:163], v[212:215], 0
	v_mfma_f32_16x16x32_bf16 v[72:75], v[164:167], v[216:219], v[72:75]
	v_mfma_f32_16x16x32_bf16 v[80:83], v[152:155], v[212:215], 0
	v_mfma_f32_16x16x32_bf16 v[80:83], v[156:159], v[216:219], v[80:83]
	v_mfma_f32_16x16x32_bf16 v[68:71], v[174:177], v[212:215], 0
	v_mfma_f32_16x16x32_bf16 v[68:71], v[178:181], v[216:219], v[68:71]
	s_setprio 0
	s_barrier
	s_sleep 2
	s_add_i32 s71, s71, s51
	v_lshl_add_u64 v[202:203], s[42:43], 0, v[2:3]
	s_mov_b32 m0, s71
	ds_read_b128 v[182:185], v171 offset:16384
	ds_read_b128 v[186:189], v171 offset:17408
	ds_read_b128 v[190:193], v171 offset:18432
	ds_read_b128 v[194:197], v171 offset:19456
	ds_read_b128 v[198:201], v171 offset:20480
	ds_read_b128 v[208:211], v171 offset:21504
	ds_read_b128 v[212:215], v171 offset:22528
	ds_read_b128 v[216:219], v171 offset:23552
	global_load_lds_dwordx4 v[202:203], off
	s_add_i32 m0, s71, 0x2000
	s_add_u32 s74, s42, 0x80000
	v_lshl_add_u64 v[204:205], s[42:43], 0, v[142:143]
	s_addc_u32 s75, s43, 0
	s_add_i32 s71, s73, s51
	global_load_lds_dwordx4 v[204:205], off
	v_lshl_add_u64 v[206:207], s[74:75], 0, v[2:3]
	s_mov_b32 m0, s71
	v_lshl_add_u64 v[220:221], s[44:45], 0, v[140:141]
	global_load_lds_dwordx4 v[206:207], off
	v_lshl_add_u64 v[206:207], s[74:75], 0, v[142:143]
	s_add_i32 m0, s71, 0x2000
	s_nop 0
	global_load_lds_dwordx4 v[206:207], off
	v_lshl_add_u64 v[206:207], s[44:45], 0, v[0:1]
	s_mov_b32 m0, s53
	s_nop 0
	global_load_lds_dwordx4 v[206:207], off
	s_mov_b32 m0, s54
	s_nop 0
	global_load_lds_dwordx4 v[220:221], off
	s_waitcnt vmcnt(8)
	s_waitcnt lgkmcnt(0)
	s_barrier
	s_setprio 1
	s_waitcnt lgkmcnt(0)
	v_mfma_f32_16x16x32_bf16 v[64:67], v[132:135], v[182:185], 0
	v_mfma_f32_16x16x32_bf16 v[64:67], v[136:139], v[186:189], v[64:67]
	v_mfma_f32_16x16x32_bf16 v[52:55], v[160:163], v[182:185], 0
	v_mfma_f32_16x16x32_bf16 v[52:55], v[164:167], v[186:189], v[52:55]
	v_mfma_f32_16x16x32_bf16 v[60:63], v[152:155], v[182:185], 0
	v_mfma_f32_16x16x32_bf16 v[60:63], v[156:159], v[186:189], v[60:63]
	v_mfma_f32_16x16x32_bf16 v[44:47], v[174:177], v[182:185], 0
	v_mfma_f32_16x16x32_bf16 v[44:47], v[178:181], v[186:189], v[44:47]
	v_mfma_f32_16x16x32_bf16 v[56:59], v[132:135], v[190:193], 0
	v_mfma_f32_16x16x32_bf16 v[56:59], v[136:139], v[194:197], v[56:59]
	v_mfma_f32_16x16x32_bf16 v[36:39], v[160:163], v[190:193], 0
	v_mfma_f32_16x16x32_bf16 v[36:39], v[164:167], v[194:197], v[36:39]
	v_mfma_f32_16x16x32_bf16 v[48:51], v[152:155], v[190:193], 0
	v_mfma_f32_16x16x32_bf16 v[48:51], v[156:159], v[194:197], v[48:51]
	v_mfma_f32_16x16x32_bf16 v[28:31], v[174:177], v[190:193], 0
	v_mfma_f32_16x16x32_bf16 v[28:31], v[178:181], v[194:197], v[28:31]
	v_mfma_f32_16x16x32_bf16 v[40:43], v[132:135], v[198:201], 0
	v_mfma_f32_16x16x32_bf16 v[40:43], v[136:139], v[208:211], v[40:43]
	v_mfma_f32_16x16x32_bf16 v[20:23], v[160:163], v[198:201], 0
	v_mfma_f32_16x16x32_bf16 v[20:23], v[164:167], v[208:211], v[20:23]
	v_mfma_f32_16x16x32_bf16 v[32:35], v[152:155], v[198:201], 0
	v_mfma_f32_16x16x32_bf16 v[32:35], v[156:159], v[208:211], v[32:35]
	v_mfma_f32_16x16x32_bf16 v[12:15], v[174:177], v[198:201], 0
	v_mfma_f32_16x16x32_bf16 v[12:15], v[178:181], v[208:211], v[12:15]
	v_mfma_f32_16x16x32_bf16 v[24:27], v[132:135], v[212:215], 0
	v_mfma_f32_16x16x32_bf16 v[24:27], v[136:139], v[216:219], v[24:27]
	v_mfma_f32_16x16x32_bf16 v[8:11], v[160:163], v[212:215], 0
	v_mfma_f32_16x16x32_bf16 v[8:11], v[164:167], v[216:219], v[8:11]
	v_mfma_f32_16x16x32_bf16 v[16:19], v[152:155], v[212:215], 0
	v_mfma_f32_16x16x32_bf16 v[16:19], v[156:159], v[216:219], v[16:19]
	v_mfma_f32_16x16x32_bf16 v[4:7], v[174:177], v[212:215], 0
	v_mfma_f32_16x16x32_bf16 v[4:7], v[178:181], v[216:219], v[4:7]
	s_setprio 0
	s_barrier
	s_sleep 2
	s_add_i32 s71, 0, 0x18000
	s_add_i32 s73, 0, 0x1c000
	v_add_u32_e32 v156, s71, v169
	v_add_u32_e32 v178, s73, v169
	ds_read_b128 v[132:135], v156
	ds_read_b128 v[136:139], v156 offset:1024
	ds_read_b128 v[152:155], v156 offset:2048
	ds_read_b128 v[156:159], v156 offset:3072
	ds_read_b128 v[160:163], v178
	ds_read_b128 v[164:167], v178 offset:1024
	ds_read_b128 v[174:177], v178 offset:2048
	ds_read_b128 v[178:181], v178 offset:3072
	s_add_u32 s44, s44, 0x80000
	s_addc_u32 s45, s45, 0
	s_mov_b32 m0, s55
	v_lshl_add_u64 v[222:223], s[44:45], 0, v[0:1]
	ds_read_b128 v[182:185], v171 offset:32768
	ds_read_b128 v[186:189], v171 offset:33792
	ds_read_b128 v[190:193], v171 offset:34816
	ds_read_b128 v[194:197], v171 offset:35840
	ds_read_b128 v[198:201], v171 offset:36864
	ds_read_b128 v[208:211], v171 offset:37888
	ds_read_b128 v[212:215], v171 offset:38912
	ds_read_b128 v[216:219], v171 offset:39936
	global_load_lds_dwordx4 v[222:223], off
	v_lshl_add_u64 v[222:223], s[44:45], 0, v[140:141]
	s_mov_b32 m0, s56
	s_nop 0
	global_load_lds_dwordx4 v[222:223], off
	s_waitcnt vmcnt(8)
	s_waitcnt lgkmcnt(0)
	s_barrier
	s_setprio 1
	s_waitcnt lgkmcnt(0)
	v_mfma_f32_16x16x32_bf16 v[128:131], v[132:135], v[182:185], v[128:131]
	v_mfma_f32_16x16x32_bf16 v[128:131], v[136:139], v[186:189], v[128:131]
	v_mfma_f32_16x16x32_bf16 v[116:119], v[160:163], v[182:185], v[116:119]
	v_mfma_f32_16x16x32_bf16 v[116:119], v[164:167], v[186:189], v[116:119]
	v_mfma_f32_16x16x32_bf16 v[124:127], v[152:155], v[182:185], v[124:127]
	v_mfma_f32_16x16x32_bf16 v[124:127], v[156:159], v[186:189], v[124:127]
	v_mfma_f32_16x16x32_bf16 v[108:111], v[174:177], v[182:185], v[108:111]
	v_mfma_f32_16x16x32_bf16 v[108:111], v[178:181], v[186:189], v[108:111]
	v_mfma_f32_16x16x32_bf16 v[120:123], v[132:135], v[190:193], v[120:123]
	v_mfma_f32_16x16x32_bf16 v[120:123], v[136:139], v[194:197], v[120:123]
	v_mfma_f32_16x16x32_bf16 v[100:103], v[160:163], v[190:193], v[100:103]
	v_mfma_f32_16x16x32_bf16 v[100:103], v[164:167], v[194:197], v[100:103]
	v_mfma_f32_16x16x32_bf16 v[112:115], v[152:155], v[190:193], v[112:115]
	v_mfma_f32_16x16x32_bf16 v[112:115], v[156:159], v[194:197], v[112:115]
	v_mfma_f32_16x16x32_bf16 v[92:95], v[174:177], v[190:193], v[92:95]
	v_mfma_f32_16x16x32_bf16 v[92:95], v[178:181], v[194:197], v[92:95]
	v_mfma_f32_16x16x32_bf16 v[104:107], v[132:135], v[198:201], v[104:107]
	v_mfma_f32_16x16x32_bf16 v[104:107], v[136:139], v[208:211], v[104:107]
	v_mfma_f32_16x16x32_bf16 v[84:87], v[160:163], v[198:201], v[84:87]
	v_mfma_f32_16x16x32_bf16 v[84:87], v[164:167], v[208:211], v[84:87]
	v_mfma_f32_16x16x32_bf16 v[96:99], v[152:155], v[198:201], v[96:99]
	v_mfma_f32_16x16x32_bf16 v[96:99], v[156:159], v[208:211], v[96:99]
	v_mfma_f32_16x16x32_bf16 v[76:79], v[174:177], v[198:201], v[76:79]
	v_mfma_f32_16x16x32_bf16 v[76:79], v[178:181], v[208:211], v[76:79]
	v_mfma_f32_16x16x32_bf16 v[88:91], v[132:135], v[212:215], v[88:91]
	v_mfma_f32_16x16x32_bf16 v[88:91], v[136:139], v[216:219], v[88:91]
	v_mfma_f32_16x16x32_bf16 v[72:75], v[160:163], v[212:215], v[72:75]
	v_mfma_f32_16x16x32_bf16 v[72:75], v[164:167], v[216:219], v[72:75]
	v_mfma_f32_16x16x32_bf16 v[80:83], v[152:155], v[212:215], v[80:83]
	v_mfma_f32_16x16x32_bf16 v[80:83], v[156:159], v[216:219], v[80:83]
	v_mfma_f32_16x16x32_bf16 v[68:71], v[174:177], v[212:215], v[68:71]
	v_mfma_f32_16x16x32_bf16 v[68:71], v[178:181], v[216:219], v[68:71]
	s_setprio 0
	s_barrier
	s_sleep 2
	s_add_i32 s44, s71, s51
	v_lshl_add_u64 v[202:203], v[202:203], 0, s[66:67]
	s_mov_b32 m0, s44
	ds_read_b128 v[182:185], v171 offset:49152
	ds_read_b128 v[186:189], v171 offset:50176
	ds_read_b128 v[190:193], v171 offset:51200
	ds_read_b128 v[194:197], v171 offset:52224
	ds_read_b128 v[198:201], v171 offset:53248
	ds_read_b128 v[208:211], v171 offset:54272
	ds_read_b128 v[212:215], v171 offset:55296
	ds_read_b128 v[216:219], v171 offset:56320
	global_load_lds_dwordx4 v[202:203], off
	s_add_i32 m0, s44, 0x2000
	s_add_u32 s42, s42, 0x80080
	v_lshl_add_u64 v[202:203], v[204:205], 0, s[66:67]
	s_addc_u32 s43, s43, 0
	s_add_i32 s44, s73, s51
	global_load_lds_dwordx4 v[202:203], off
	v_lshl_add_u64 v[202:203], s[42:43], 0, v[2:3]
	s_mov_b32 m0, s44
	s_nop 0
	global_load_lds_dwordx4 v[202:203], off
	v_lshl_add_u64 v[202:203], s[42:43], 0, v[142:143]
	s_add_i32 m0, s44, 0x2000
	s_nop 0
	global_load_lds_dwordx4 v[202:203], off
	v_lshl_add_u64 v[202:203], v[206:207], 0, s[66:67]
	s_mov_b32 m0, s65
	s_nop 0
	global_load_lds_dwordx4 v[202:203], off
	v_lshl_add_u64 v[202:203], v[220:221], 0, s[66:67]
	s_mov_b32 m0, s68
	s_nop 0
	global_load_lds_dwordx4 v[202:203], off
	s_waitcnt vmcnt(8)
	s_waitcnt lgkmcnt(0)
	s_barrier
	s_setprio 1
	s_waitcnt lgkmcnt(0)
	v_mfma_f32_16x16x32_bf16 v[64:67], v[132:135], v[182:185], v[64:67]
	v_mfma_f32_16x16x32_bf16 v[64:67], v[136:139], v[186:189], v[64:67]
	v_mfma_f32_16x16x32_bf16 v[52:55], v[160:163], v[182:185], v[52:55]
	v_mfma_f32_16x16x32_bf16 v[52:55], v[164:167], v[186:189], v[52:55]
	v_mfma_f32_16x16x32_bf16 v[60:63], v[152:155], v[182:185], v[60:63]
	v_mfma_f32_16x16x32_bf16 v[60:63], v[156:159], v[186:189], v[60:63]
	v_mfma_f32_16x16x32_bf16 v[44:47], v[174:177], v[182:185], v[44:47]
	v_mfma_f32_16x16x32_bf16 v[44:47], v[178:181], v[186:189], v[44:47]
	v_mfma_f32_16x16x32_bf16 v[56:59], v[132:135], v[190:193], v[56:59]
	v_mfma_f32_16x16x32_bf16 v[56:59], v[136:139], v[194:197], v[56:59]
	v_mfma_f32_16x16x32_bf16 v[36:39], v[160:163], v[190:193], v[36:39]
	v_mfma_f32_16x16x32_bf16 v[36:39], v[164:167], v[194:197], v[36:39]
	v_mfma_f32_16x16x32_bf16 v[48:51], v[152:155], v[190:193], v[48:51]
	v_mfma_f32_16x16x32_bf16 v[48:51], v[156:159], v[194:197], v[48:51]
	v_mfma_f32_16x16x32_bf16 v[28:31], v[174:177], v[190:193], v[28:31]
	v_mfma_f32_16x16x32_bf16 v[28:31], v[178:181], v[194:197], v[28:31]
	v_mfma_f32_16x16x32_bf16 v[40:43], v[132:135], v[198:201], v[40:43]
	v_mfma_f32_16x16x32_bf16 v[40:43], v[136:139], v[208:211], v[40:43]
	v_mfma_f32_16x16x32_bf16 v[20:23], v[160:163], v[198:201], v[20:23]
	v_mfma_f32_16x16x32_bf16 v[20:23], v[164:167], v[208:211], v[20:23]
	v_mfma_f32_16x16x32_bf16 v[32:35], v[152:155], v[198:201], v[32:35]
	v_mfma_f32_16x16x32_bf16 v[32:35], v[156:159], v[208:211], v[32:35]
	v_mfma_f32_16x16x32_bf16 v[12:15], v[174:177], v[198:201], v[12:15]
	v_mfma_f32_16x16x32_bf16 v[12:15], v[178:181], v[208:211], v[12:15]
	v_mfma_f32_16x16x32_bf16 v[24:27], v[132:135], v[212:215], v[24:27]
	v_mfma_f32_16x16x32_bf16 v[24:27], v[136:139], v[216:219], v[24:27]
	v_mfma_f32_16x16x32_bf16 v[8:11], v[160:163], v[212:215], v[8:11]
	v_mfma_f32_16x16x32_bf16 v[8:11], v[164:167], v[216:219], v[8:11]
	v_mfma_f32_16x16x32_bf16 v[16:19], v[152:155], v[212:215], v[16:19]
	v_mfma_f32_16x16x32_bf16 v[16:19], v[156:159], v[216:219], v[16:19]
	v_mfma_f32_16x16x32_bf16 v[4:7], v[174:177], v[212:215], v[4:7]
	v_mfma_f32_16x16x32_bf16 v[4:7], v[178:181], v[216:219], v[4:7]
	s_setprio 0
	s_barrier
	s_add_i32 s63, s63, 2
	s_add_u32 s40, s40, 0x100
	s_addc_u32 s41, s41, 0
	s_add_u32 s31, s31, 0x100
	s_addc_u32 s62, s62, 0
	s_cmp_gt_u32 s63, 29

.LBB0_210:
	s_ashr_i32 s21, s20, 31
	s_lshl_b64 s[22:23], s[20:21], 20
	s_add_u32 s22, s4, s22
	s_addc_u32 s23, s5, s23
	s_and_b64 s[24:25], s[34:35], exec
	s_cselect_b32 s21, s23, s29
	s_cselect_b32 s53, s22, s28
	s_ashr_i32 s19, s18, 31
	s_lshl_b64 s[24:25], s[18:19], 20
	s_add_u32 s24, s2, s24
	s_addc_u32 s25, s40, s25
	s_and_b64 s[38:39], s[34:35], exec
	s_cselect_b32 s19, s25, s31
	s_cselect_b32 s54, s24, s30
	s_add_u32 s28, s28, 0x80080
	s_addc_u32 s29, s29, 0
	s_add_u32 s55, s30, 0x100
	s_addc_u32 s56, s31, 0
	s_mov_b32 s57, -2
	s_sleep 2
	s_add_u32 s30, s28, 0xfff80080
	s_addc_u32 s31, s29, -1
	s_add_i32 s58, 0, 0x10000
	s_cmp_eq_u32 s57, 28
	s_cselect_b32 s39, s21, s31
	s_cselect_b32 s38, s53, s30
	v_add_u32_e32 v148, s58, v151
	s_cselect_b32 s31, s19, s56
	s_cselect_b32 s30, s54, s55
	s_add_i32 s60, 0, 0x14000
	ds_read_b128 v[140:143], v148
	ds_read_b128 v[144:147], v148 offset:1024
	ds_read_b128 v[156:159], v148 offset:2048
	ds_read_b128 v[160:163], v148 offset:3072
	v_add_u32_e32 v148, s60, v151
	ds_read_b128 v[164:167], v148
	ds_read_b128 v[168:171], v148 offset:1024
	ds_read_b128 v[172:175], v148 offset:2048
	ds_read_b128 v[176:179], v148 offset:3072
	s_add_i32 m0, s43, 0xc000
	ds_read_b128 v[180:183], v154
	ds_read_b128 v[184:187], v154 offset:1024
	ds_read_b128 v[188:191], v154 offset:2048
	ds_read_b128 v[192:195], v154 offset:3072
	ds_read_b128 v[196:199], v154 offset:4096
	ds_read_b128 v[200:203], v154 offset:5120
	ds_read_b128 v[208:211], v154 offset:6144
	ds_read_b128 v[212:215], v154 offset:7168
	global_load_lds_dwordx4 v136, s[28:29]
	s_add_i32 m0, s43, 0xe000
	s_nop 0
	global_load_lds_dwordx4 v138, s[28:29]
	s_waitcnt vmcnt(8)
	s_waitcnt lgkmcnt(0)
	s_barrier
	s_setprio 1
	s_waitcnt lgkmcnt(0)
	v_mfma_f32_16x16x32_bf16 v[128:131], v[140:143], v[180:183], 0
	v_mfma_f32_16x16x32_bf16 v[128:131], v[144:147], v[184:187], v[128:131]
	v_mfma_f32_16x16x32_bf16 v[120:123], v[164:167], v[180:183], 0
	v_mfma_f32_16x16x32_bf16 v[120:123], v[168:171], v[184:187], v[120:123]
	v_mfma_f32_16x16x32_bf16 v[124:127], v[156:159], v[180:183], 0
	v_mfma_f32_16x16x32_bf16 v[124:127], v[160:163], v[184:187], v[124:127]
	v_mfma_f32_16x16x32_bf16 v[116:119], v[172:175], v[180:183], 0
	v_mfma_f32_16x16x32_bf16 v[116:119], v[176:179], v[184:187], v[116:119]
	v_mfma_f32_16x16x32_bf16 v[112:115], v[140:143], v[188:191], 0
	v_mfma_f32_16x16x32_bf16 v[112:115], v[144:147], v[192:195], v[112:115]
	v_mfma_f32_16x16x32_bf16 v[104:107], v[164:167], v[188:191], 0
	v_mfma_f32_16x16x32_bf16 v[104:107], v[168:171], v[192:195], v[104:107]
	v_mfma_f32_16x16x32_bf16 v[108:111], v[156:159], v[188:191], 0
	v_mfma_f32_16x16x32_bf16 v[108:111], v[160:163], v[192:195], v[108:111]
	v_mfma_f32_16x16x32_bf16 v[100:103], v[172:175], v[188:191], 0
	v_mfma_f32_16x16x32_bf16 v[100:103], v[176:179], v[192:195], v[100:103]
	v_mfma_f32_16x16x32_bf16 v[96:99], v[140:143], v[196:199], 0
	v_mfma_f32_16x16x32_bf16 v[96:99], v[144:147], v[200:203], v[96:99]
	v_mfma_f32_16x16x32_bf16 v[88:91], v[164:167], v[196:199], 0
	v_mfma_f32_16x16x32_bf16 v[88:91], v[168:171], v[200:203], v[88:91]
	v_mfma_f32_16x16x32_bf16 v[92:95], v[156:159], v[196:199], 0
	v_mfma_f32_16x16x32_bf16 v[92:95], v[160:163], v[200:203], v[92:95]
	v_mfma_f32_16x16x32_bf16 v[84:87], v[172:175], v[196:199], 0
	v_mfma_f32_16x16x32_bf16 v[84:87], v[176:179], v[200:203], v[84:87]
	v_mfma_f32_16x16x32_bf16 v[80:83], v[140:143], v[208:211], 0
	v_mfma_f32_16x16x32_bf16 v[80:83], v[144:147], v[212:215], v[80:83]
	v_mfma_f32_16x16x32_bf16 v[72:75], v[164:167], v[208:211], 0
	v_mfma_f32_16x16x32_bf16 v[72:75], v[168:171], v[212:215], v[72:75]
	v_mfma_f32_16x16x32_bf16 v[76:79], v[156:159], v[208:211], 0
	v_mfma_f32_16x16x32_bf16 v[76:79], v[160:163], v[212:215], v[76:79]
	v_mfma_f32_16x16x32_bf16 v[68:71], v[172:175], v[208:211], 0
	v_mfma_f32_16x16x32_bf16 v[68:71], v[176:179], v[212:215], v[68:71]
	s_setprio 0
	s_barrier
	s_sleep 2
	s_add_i32 s58, s58, s41
	s_mov_b32 m0, s58
	ds_read_b128 v[180:183], v154 offset:16384
	ds_read_b128 v[184:187], v154 offset:17408
	ds_read_b128 v[188:191], v154 offset:18432
	ds_read_b128 v[192:195], v154 offset:19456
	ds_read_b128 v[196:199], v154 offset:20480
	ds_read_b128 v[200:203], v154 offset:21504
	ds_read_b128 v[208:211], v154 offset:22528
	ds_read_b128 v[212:215], v154 offset:23552
	global_load_lds_dwordx4 v2, s[30:31]
	s_add_i32 m0, s58, 0x2000
	s_add_u32 s62, s30, 0x80000
	s_addc_u32 s63, s31, 0
	s_add_i32 s58, s60, s41
	global_load_lds_dwordx4 v0, s[30:31]
	s_mov_b32 m0, s58
	s_nop 0
	global_load_lds_dwordx4 v2, s[62:63]
	s_add_i32 m0, s58, 0x2000
	s_nop 0
	global_load_lds_dwordx4 v0, s[62:63]
	s_mov_b32 m0, s43
	s_nop 0
	global_load_lds_dwordx4 v134, s[38:39]
	s_mov_b32 m0, s44
	s_nop 0
	global_load_lds_dwordx4 v132, s[38:39]
	s_waitcnt vmcnt(8)
	s_waitcnt lgkmcnt(0)
	s_barrier
	s_setprio 1
	s_waitcnt lgkmcnt(0)
	v_mfma_f32_16x16x32_bf16 v[64:67], v[140:143], v[180:183], 0
	v_mfma_f32_16x16x32_bf16 v[64:67], v[144:147], v[184:187], v[64:67]
	v_mfma_f32_16x16x32_bf16 v[56:59], v[164:167], v[180:183], 0
	v_mfma_f32_16x16x32_bf16 v[56:59], v[168:171], v[184:187], v[56:59]
	v_mfma_f32_16x16x32_bf16 v[60:63], v[156:159], v[180:183], 0
	v_mfma_f32_16x16x32_bf16 v[60:63], v[160:163], v[184:187], v[60:63]
	v_mfma_f32_16x16x32_bf16 v[52:55], v[172:175], v[180:183], 0
	v_mfma_f32_16x16x32_bf16 v[52:55], v[176:179], v[184:187], v[52:55]
	v_mfma_f32_16x16x32_bf16 v[48:51], v[140:143], v[188:191], 0
	v_mfma_f32_16x16x32_bf16 v[48:51], v[144:147], v[192:195], v[48:51]
	v_mfma_f32_16x16x32_bf16 v[40:43], v[164:167], v[188:191], 0
	v_mfma_f32_16x16x32_bf16 v[40:43], v[168:171], v[192:195], v[40:43]
	v_mfma_f32_16x16x32_bf16 v[44:47], v[156:159], v[188:191], 0
	v_mfma_f32_16x16x32_bf16 v[44:47], v[160:163], v[192:195], v[44:47]
	v_mfma_f32_16x16x32_bf16 v[36:39], v[172:175], v[188:191], 0
	v_mfma_f32_16x16x32_bf16 v[36:39], v[176:179], v[192:195], v[36:39]
	v_mfma_f32_16x16x32_bf16 v[32:35], v[140:143], v[196:199], 0
	v_mfma_f32_16x16x32_bf16 v[32:35], v[144:147], v[200:203], v[32:35]
	v_mfma_f32_16x16x32_bf16 v[24:27], v[164:167], v[196:199], 0
	v_mfma_f32_16x16x32_bf16 v[24:27], v[168:171], v[200:203], v[24:27]
	v_mfma_f32_16x16x32_bf16 v[28:31], v[156:159], v[196:199], 0
	v_mfma_f32_16x16x32_bf16 v[28:31], v[160:163], v[200:203], v[28:31]
	v_mfma_f32_16x16x32_bf16 v[20:23], v[172:175], v[196:199], 0
	v_mfma_f32_16x16x32_bf16 v[20:23], v[176:179], v[200:203], v[20:23]
	v_mfma_f32_16x16x32_bf16 v[16:19], v[140:143], v[208:211], 0
	v_mfma_f32_16x16x32_bf16 v[16:19], v[144:147], v[212:215], v[16:19]
	v_mfma_f32_16x16x32_bf16 v[8:11], v[164:167], v[208:211], 0
	v_mfma_f32_16x16x32_bf16 v[8:11], v[168:171], v[212:215], v[8:11]
	v_mfma_f32_16x16x32_bf16 v[12:15], v[156:159], v[208:211], 0
	v_mfma_f32_16x16x32_bf16 v[12:15], v[160:163], v[212:215], v[12:15]
	v_mfma_f32_16x16x32_bf16 v[4:7], v[172:175], v[208:211], 0
	v_mfma_f32_16x16x32_bf16 v[4:7], v[176:179], v[212:215], v[4:7]
	s_setprio 0
	s_barrier
	s_sleep 2
	s_add_i32 s58, 0, 0x18000
	v_add_u32_e32 v155, s58, v151
	s_add_i32 s60, 0, 0x1c000
	ds_read_b128 v[140:143], v155
	ds_read_b128 v[144:147], v155 offset:1024
	ds_read_b128 v[156:159], v155 offset:2048
	ds_read_b128 v[160:163], v155 offset:3072
	v_add_u32_e32 v155, s60, v151
	ds_read_b128 v[164:167], v155
	ds_read_b128 v[168:171], v155 offset:1024
	ds_read_b128 v[172:175], v155 offset:2048
	ds_read_b128 v[176:179], v155 offset:3072
	s_add_u32 s38, s38, 0x80000
	s_addc_u32 s39, s39, 0
	s_mov_b32 m0, s45
	ds_read_b128 v[180:183], v154 offset:32768
	ds_read_b128 v[184:187], v154 offset:33792
	ds_read_b128 v[188:191], v154 offset:34816
	ds_read_b128 v[192:195], v154 offset:35840
	ds_read_b128 v[196:199], v154 offset:36864
	ds_read_b128 v[200:203], v154 offset:37888
	ds_read_b128 v[208:211], v154 offset:38912
	ds_read_b128 v[212:215], v154 offset:39936
	global_load_lds_dwordx4 v134, s[38:39]
	s_mov_b32 m0, s47
	s_nop 0
	global_load_lds_dwordx4 v132, s[38:39]
	s_waitcnt vmcnt(8)
	s_waitcnt lgkmcnt(0)
	s_barrier
	s_setprio 1
	s_waitcnt lgkmcnt(0)
	v_mfma_f32_16x16x32_bf16 v[128:131], v[140:143], v[180:183], v[128:131]
	v_mfma_f32_16x16x32_bf16 v[128:131], v[144:147], v[184:187], v[128:131]
	v_mfma_f32_16x16x32_bf16 v[120:123], v[164:167], v[180:183], v[120:123]
	v_mfma_f32_16x16x32_bf16 v[120:123], v[168:171], v[184:187], v[120:123]
	v_mfma_f32_16x16x32_bf16 v[124:127], v[156:159], v[180:183], v[124:127]
	v_mfma_f32_16x16x32_bf16 v[124:127], v[160:163], v[184:187], v[124:127]
	v_mfma_f32_16x16x32_bf16 v[116:119], v[172:175], v[180:183], v[116:119]
	v_mfma_f32_16x16x32_bf16 v[116:119], v[176:179], v[184:187], v[116:119]
	v_mfma_f32_16x16x32_bf16 v[112:115], v[140:143], v[188:191], v[112:115]
	v_mfma_f32_16x16x32_bf16 v[112:115], v[144:147], v[192:195], v[112:115]
	v_mfma_f32_16x16x32_bf16 v[104:107], v[164:167], v[188:191], v[104:107]
	v_mfma_f32_16x16x32_bf16 v[104:107], v[168:171], v[192:195], v[104:107]
	v_mfma_f32_16x16x32_bf16 v[108:111], v[156:159], v[188:191], v[108:111]
	v_mfma_f32_16x16x32_bf16 v[108:111], v[160:163], v[192:195], v[108:111]
	v_mfma_f32_16x16x32_bf16 v[100:103], v[172:175], v[188:191], v[100:103]
	v_mfma_f32_16x16x32_bf16 v[100:103], v[176:179], v[192:195], v[100:103]
	v_mfma_f32_16x16x32_bf16 v[96:99], v[140:143], v[196:199], v[96:99]
	v_mfma_f32_16x16x32_bf16 v[96:99], v[144:147], v[200:203], v[96:99]
	v_mfma_f32_16x16x32_bf16 v[88:91], v[164:167], v[196:199], v[88:91]
	v_mfma_f32_16x16x32_bf16 v[88:91], v[168:171], v[200:203], v[88:91]
	v_mfma_f32_16x16x32_bf16 v[92:95], v[156:159], v[196:199], v[92:95]
	v_mfma_f32_16x16x32_bf16 v[92:95], v[160:163], v[200:203], v[92:95]
	v_mfma_f32_16x16x32_bf16 v[84:87], v[172:175], v[196:199], v[84:87]
	v_mfma_f32_16x16x32_bf16 v[84:87], v[176:179], v[200:203], v[84:87]
	v_mfma_f32_16x16x32_bf16 v[80:83], v[140:143], v[208:211], v[80:83]
	v_mfma_f32_16x16x32_bf16 v[80:83], v[144:147], v[212:215], v[80:83]
	v_mfma_f32_16x16x32_bf16 v[72:75], v[164:167], v[208:211], v[72:75]
	v_mfma_f32_16x16x32_bf16 v[72:75], v[168:171], v[212:215], v[72:75]
	v_mfma_f32_16x16x32_bf16 v[76:79], v[156:159], v[208:211], v[76:79]
	v_mfma_f32_16x16x32_bf16 v[76:79], v[160:163], v[212:215], v[76:79]
	v_mfma_f32_16x16x32_bf16 v[68:71], v[172:175], v[208:211], v[68:71]
	v_mfma_f32_16x16x32_bf16 v[68:71], v[176:179], v[212:215], v[68:71]
	s_setprio 0
	s_barrier
	s_sleep 2
	s_add_i32 s62, s58, s41
	s_add_u32 s30, s30, 0x80
	s_addc_u32 s31, s31, 0
	s_mov_b32 m0, s62
	ds_read_b128 v[180:183], v154 offset:49152
	ds_read_b128 v[184:187], v154 offset:50176
	ds_read_b128 v[188:191], v154 offset:51200
	ds_read_b128 v[192:195], v154 offset:52224
	ds_read_b128 v[196:199], v154 offset:53248
	ds_read_b128 v[200:203], v154 offset:54272
	ds_read_b128 v[208:211], v154 offset:55296
	ds_read_b128 v[212:215], v154 offset:56320
	global_load_lds_dwordx4 v2, s[30:31]
	s_add_i32 m0, s62, 0x2000
	s_nop 0
	s_add_i32 s62, s60, s41
	global_load_lds_dwordx4 v0, s[30:31]
	s_add_u32 s30, s30, 0x80000
	s_addc_u32 s31, s31, 0
	s_mov_b32 m0, s62
	s_nop 0
	global_load_lds_dwordx4 v2, s[30:31]
	s_add_i32 m0, s62, 0x2000
	s_nop 0
	global_load_lds_dwordx4 v0, s[30:31]
	s_sub_u32 s38, s38, 0x7ff80
	s_subb_u32 s39, s39, 0
	s_mov_b32 m0, s48
	s_nop 0
	global_load_lds_dwordx4 v134, s[38:39]
	s_mov_b32 m0, s49
	s_nop 0
	global_load_lds_dwordx4 v132, s[38:39]
	s_waitcnt vmcnt(8)
	s_waitcnt lgkmcnt(0)
	s_barrier
	s_setprio 1
	s_waitcnt lgkmcnt(0)
	v_mfma_f32_16x16x32_bf16 v[64:67], v[140:143], v[180:183], v[64:67]
	v_mfma_f32_16x16x32_bf16 v[64:67], v[144:147], v[184:187], v[64:67]
	v_mfma_f32_16x16x32_bf16 v[56:59], v[164:167], v[180:183], v[56:59]
	v_mfma_f32_16x16x32_bf16 v[56:59], v[168:171], v[184:187], v[56:59]
	v_mfma_f32_16x16x32_bf16 v[60:63], v[156:159], v[180:183], v[60:63]
	v_mfma_f32_16x16x32_bf16 v[60:63], v[160:163], v[184:187], v[60:63]
	v_mfma_f32_16x16x32_bf16 v[52:55], v[172:175], v[180:183], v[52:55]
	v_mfma_f32_16x16x32_bf16 v[52:55], v[176:179], v[184:187], v[52:55]
	v_mfma_f32_16x16x32_bf16 v[48:51], v[140:143], v[188:191], v[48:51]
	v_mfma_f32_16x16x32_bf16 v[48:51], v[144:147], v[192:195], v[48:51]
	v_mfma_f32_16x16x32_bf16 v[40:43], v[164:167], v[188:191], v[40:43]
	v_mfma_f32_16x16x32_bf16 v[40:43], v[168:171], v[192:195], v[40:43]
	v_mfma_f32_16x16x32_bf16 v[44:47], v[156:159], v[188:191], v[44:47]
	v_mfma_f32_16x16x32_bf16 v[44:47], v[160:163], v[192:195], v[44:47]
	v_mfma_f32_16x16x32_bf16 v[36:39], v[172:175], v[188:191], v[36:39]
	v_mfma_f32_16x16x32_bf16 v[36:39], v[176:179], v[192:195], v[36:39]
	v_mfma_f32_16x16x32_bf16 v[32:35], v[140:143], v[196:199], v[32:35]
	v_mfma_f32_16x16x32_bf16 v[32:35], v[144:147], v[200:203], v[32:35]
	v_mfma_f32_16x16x32_bf16 v[24:27], v[164:167], v[196:199], v[24:27]
	v_mfma_f32_16x16x32_bf16 v[24:27], v[168:171], v[200:203], v[24:27]
	v_mfma_f32_16x16x32_bf16 v[28:31], v[156:159], v[196:199], v[28:31]
	v_mfma_f32_16x16x32_bf16 v[28:31], v[160:163], v[200:203], v[28:31]
	v_mfma_f32_16x16x32_bf16 v[20:23], v[172:175], v[196:199], v[20:23]
	v_mfma_f32_16x16x32_bf16 v[20:23], v[176:179], v[200:203], v[20:23]
	v_mfma_f32_16x16x32_bf16 v[16:19], v[140:143], v[208:211], v[16:19]
	v_mfma_f32_16x16x32_bf16 v[16:19], v[144:147], v[212:215], v[16:19]
	v_mfma_f32_16x16x32_bf16 v[8:11], v[164:167], v[208:211], v[8:11]
	v_mfma_f32_16x16x32_bf16 v[8:11], v[168:171], v[212:215], v[8:11]
	v_mfma_f32_16x16x32_bf16 v[12:15], v[156:159], v[208:211], v[12:15]
	v_mfma_f32_16x16x32_bf16 v[12:15], v[160:163], v[212:215], v[12:15]
	v_mfma_f32_16x16x32_bf16 v[4:7], v[172:175], v[208:211], v[4:7]
	v_mfma_f32_16x16x32_bf16 v[4:7], v[176:179], v[212:215], v[4:7]
	s_setprio 0
	s_barrier
	s_add_i32 s57, s57, 2
	s_add_u32 s28, s28, 0x100
	s_addc_u32 s29, s29, 0
	s_add_u32 s55, s55, 0x100
	s_addc_u32 s56, s56, 0
	s_cmp_gt_u32 s57, 29

.LBB0_300:
	s_add_u32 s40, s18, 0x100
	s_addc_u32 s41, s19, 0
	s_mov_b32 s48, -2
	s_sleep 2
	s_add_u32 s18, s16, 0x100
	s_addc_u32 s19, s17, 0
	s_add_i32 s49, 0, 0x10000
	s_cmpk_eq_i32 s48, 0x54
	s_cselect_b32 s23, s13, s19
	s_cselect_b32 s22, s12, s18
	s_cselect_b32 s21, s15, s41
	s_cselect_b32 s20, s14, s40
	s_add_i32 s50, 0, 0x14000
	v_add_u32_e32 v144, s49, v219
	v_add_u32_e32 v160, s50, v219
	ds_read_b128 v[124:127], v144
	ds_read_b128 v[128:131], v144 offset:1024
	ds_read_b128 v[140:143], v144 offset:2048
	ds_read_b128 v[144:147], v144 offset:3072
	ds_read_b128 v[148:151], v160
	ds_read_b128 v[152:155], v160 offset:1024
	ds_read_b128 v[156:159], v160 offset:2048
	ds_read_b128 v[160:163], v160 offset:3072
	v_lshl_add_u64 v[204:205], s[16:17], 0, v[192:193]
	s_add_i32 m0, s28, 0xc000
	ds_read_b128 v[164:167], v221
	ds_read_b128 v[168:171], v221 offset:1024
	ds_read_b128 v[172:175], v221 offset:2048
	ds_read_b128 v[176:179], v221 offset:3072
	ds_read_b128 v[180:183], v221 offset:4096
	ds_read_b128 v[184:187], v221 offset:5120
	ds_read_b128 v[196:199], v221 offset:6144
	ds_read_b128 v[200:203], v221 offset:7168
	global_load_lds_dwordx4 v[204:205], off
	v_lshl_add_u64 v[204:205], s[16:17], 0, v[194:195]
	s_add_i32 m0, s28, 0xe000
	s_nop 0
	global_load_lds_dwordx4 v[204:205], off
	s_waitcnt vmcnt(8)
	s_waitcnt lgkmcnt(0)
	s_barrier
	s_setprio 1
	s_waitcnt lgkmcnt(0)
	v_mfma_f32_16x16x32_bf16 v[136:139], v[124:127], v[164:167], 0
	v_mfma_f32_16x16x32_bf16 v[136:139], v[128:131], v[168:171], v[136:139]
	v_mfma_f32_16x16x32_bf16 v[120:123], v[148:151], v[164:167], 0
	v_mfma_f32_16x16x32_bf16 v[120:123], v[152:155], v[168:171], v[120:123]
	v_mfma_f32_16x16x32_bf16 v[132:135], v[140:143], v[164:167], 0
	v_mfma_f32_16x16x32_bf16 v[132:135], v[144:147], v[168:171], v[132:135]
	v_mfma_f32_16x16x32_bf16 v[116:119], v[156:159], v[164:167], 0
	v_mfma_f32_16x16x32_bf16 v[116:119], v[160:163], v[168:171], v[116:119]
	v_mfma_f32_16x16x32_bf16 v[112:115], v[124:127], v[172:175], 0
	v_mfma_f32_16x16x32_bf16 v[112:115], v[128:131], v[176:179], v[112:115]
	v_mfma_f32_16x16x32_bf16 v[104:107], v[148:151], v[172:175], 0
	v_mfma_f32_16x16x32_bf16 v[104:107], v[152:155], v[176:179], v[104:107]
	v_mfma_f32_16x16x32_bf16 v[108:111], v[140:143], v[172:175], 0
	v_mfma_f32_16x16x32_bf16 v[108:111], v[144:147], v[176:179], v[108:111]
	v_mfma_f32_16x16x32_bf16 v[100:103], v[156:159], v[172:175], 0
	v_mfma_f32_16x16x32_bf16 v[100:103], v[160:163], v[176:179], v[100:103]
	v_mfma_f32_16x16x32_bf16 v[96:99], v[124:127], v[180:183], 0
	v_mfma_f32_16x16x32_bf16 v[96:99], v[128:131], v[184:187], v[96:99]
	v_mfma_f32_16x16x32_bf16 v[88:91], v[148:151], v[180:183], 0
	v_mfma_f32_16x16x32_bf16 v[88:91], v[152:155], v[184:187], v[88:91]
	v_mfma_f32_16x16x32_bf16 v[92:95], v[140:143], v[180:183], 0
	v_mfma_f32_16x16x32_bf16 v[92:95], v[144:147], v[184:187], v[92:95]
	v_mfma_f32_16x16x32_bf16 v[84:87], v[156:159], v[180:183], 0
	v_mfma_f32_16x16x32_bf16 v[84:87], v[160:163], v[184:187], v[84:87]
	v_mfma_f32_16x16x32_bf16 v[80:83], v[124:127], v[196:199], 0
	v_mfma_f32_16x16x32_bf16 v[80:83], v[128:131], v[200:203], v[80:83]
	v_mfma_f32_16x16x32_bf16 v[72:75], v[148:151], v[196:199], 0
	v_mfma_f32_16x16x32_bf16 v[72:75], v[152:155], v[200:203], v[72:75]
	v_mfma_f32_16x16x32_bf16 v[76:79], v[140:143], v[196:199], 0
	v_mfma_f32_16x16x32_bf16 v[76:79], v[144:147], v[200:203], v[76:79]
	v_mfma_f32_16x16x32_bf16 v[68:71], v[156:159], v[196:199], 0
	v_mfma_f32_16x16x32_bf16 v[68:71], v[160:163], v[200:203], v[68:71]
	s_setprio 0
	s_barrier
	s_sleep 2
	s_add_i32 s16, s49, s2
	v_lshl_add_u64 v[204:205], s[20:21], 0, v[2:3]
	s_mov_b32 m0, s16
	ds_read_b128 v[164:167], v221 offset:16384
	ds_read_b128 v[168:171], v221 offset:17408
	ds_read_b128 v[172:175], v221 offset:18432
	ds_read_b128 v[176:179], v221 offset:19456
	ds_read_b128 v[180:183], v221 offset:20480
	ds_read_b128 v[184:187], v221 offset:21504
	ds_read_b128 v[196:199], v221 offset:22528
	ds_read_b128 v[200:203], v221 offset:23552
	global_load_lds_dwordx4 v[204:205], off
	s_add_i32 m0, s16, 0x2000
	s_add_u32 s16, s20, 0x160000
	v_lshl_add_u64 v[206:207], s[20:21], 0, v[190:191]
	s_addc_u32 s17, s21, 0
	s_add_i32 s49, s50, s2
	global_load_lds_dwordx4 v[206:207], off
	v_lshl_add_u64 v[208:209], s[16:17], 0, v[2:3]
	s_mov_b32 m0, s49
	v_lshl_add_u64 v[210:211], s[22:23], 0, v[188:189]
	global_load_lds_dwordx4 v[208:209], off
	v_lshl_add_u64 v[208:209], s[16:17], 0, v[190:191]
	s_add_i32 m0, s49, 0x2000
	s_nop 0
	global_load_lds_dwordx4 v[208:209], off
	v_lshl_add_u64 v[208:209], s[22:23], 0, v[0:1]
	s_mov_b32 m0, s28
	s_nop 0
	global_load_lds_dwordx4 v[208:209], off
	s_mov_b32 m0, s29
	s_nop 0
	global_load_lds_dwordx4 v[210:211], off
	s_waitcnt vmcnt(8)
	s_waitcnt lgkmcnt(0)
	s_barrier
	s_setprio 1
	s_waitcnt lgkmcnt(0)
	v_mfma_f32_16x16x32_bf16 v[64:67], v[124:127], v[164:167], 0
	v_mfma_f32_16x16x32_bf16 v[64:67], v[128:131], v[168:171], v[64:67]
	v_mfma_f32_16x16x32_bf16 v[56:59], v[148:151], v[164:167], 0
	v_mfma_f32_16x16x32_bf16 v[56:59], v[152:155], v[168:171], v[56:59]
	v_mfma_f32_16x16x32_bf16 v[60:63], v[140:143], v[164:167], 0
	v_mfma_f32_16x16x32_bf16 v[60:63], v[144:147], v[168:171], v[60:63]
	v_mfma_f32_16x16x32_bf16 v[52:55], v[156:159], v[164:167], 0
	v_mfma_f32_16x16x32_bf16 v[52:55], v[160:163], v[168:171], v[52:55]
	v_mfma_f32_16x16x32_bf16 v[48:51], v[124:127], v[172:175], 0
	v_mfma_f32_16x16x32_bf16 v[48:51], v[128:131], v[176:179], v[48:51]
	v_mfma_f32_16x16x32_bf16 v[40:43], v[148:151], v[172:175], 0
	v_mfma_f32_16x16x32_bf16 v[40:43], v[152:155], v[176:179], v[40:43]
	v_mfma_f32_16x16x32_bf16 v[44:47], v[140:143], v[172:175], 0
	v_mfma_f32_16x16x32_bf16 v[44:47], v[144:147], v[176:179], v[44:47]
	v_mfma_f32_16x16x32_bf16 v[36:39], v[156:159], v[172:175], 0
	v_mfma_f32_16x16x32_bf16 v[36:39], v[160:163], v[176:179], v[36:39]
	v_mfma_f32_16x16x32_bf16 v[32:35], v[124:127], v[180:183], 0
	v_mfma_f32_16x16x32_bf16 v[32:35], v[128:131], v[184:187], v[32:35]
	v_mfma_f32_16x16x32_bf16 v[24:27], v[148:151], v[180:183], 0
	v_mfma_f32_16x16x32_bf16 v[24:27], v[152:155], v[184:187], v[24:27]
	v_mfma_f32_16x16x32_bf16 v[28:31], v[140:143], v[180:183], 0
	v_mfma_f32_16x16x32_bf16 v[28:31], v[144:147], v[184:187], v[28:31]
	v_mfma_f32_16x16x32_bf16 v[20:23], v[156:159], v[180:183], 0
	v_mfma_f32_16x16x32_bf16 v[20:23], v[160:163], v[184:187], v[20:23]
	v_mfma_f32_16x16x32_bf16 v[16:19], v[124:127], v[196:199], 0
	v_mfma_f32_16x16x32_bf16 v[16:19], v[128:131], v[200:203], v[16:19]
	v_mfma_f32_16x16x32_bf16 v[8:11], v[148:151], v[196:199], 0
	v_mfma_f32_16x16x32_bf16 v[8:11], v[152:155], v[200:203], v[8:11]
	v_mfma_f32_16x16x32_bf16 v[12:15], v[140:143], v[196:199], 0
	v_mfma_f32_16x16x32_bf16 v[12:15], v[144:147], v[200:203], v[12:15]
	v_mfma_f32_16x16x32_bf16 v[4:7], v[156:159], v[196:199], 0
	v_mfma_f32_16x16x32_bf16 v[4:7], v[160:163], v[200:203], v[4:7]
	s_setprio 0
	s_barrier
	s_sleep 2
	s_add_i32 s49, 0, 0x18000
	s_add_i32 s50, 0, 0x1c000
	v_add_u32_e32 v144, s49, v219
	v_add_u32_e32 v160, s50, v219
	ds_read_b128 v[124:127], v144
	ds_read_b128 v[128:131], v144 offset:1024
	ds_read_b128 v[140:143], v144 offset:2048
	ds_read_b128 v[144:147], v144 offset:3072
	ds_read_b128 v[148:151], v160
	ds_read_b128 v[152:155], v160 offset:1024
	ds_read_b128 v[156:159], v160 offset:2048
	ds_read_b128 v[160:163], v160 offset:3072
	s_add_u32 s16, s22, 0x160000
	s_addc_u32 s17, s23, 0
	s_mov_b32 m0, s30
	v_lshl_add_u64 v[212:213], s[16:17], 0, v[0:1]
	ds_read_b128 v[164:167], v221 offset:32768
	ds_read_b128 v[168:171], v221 offset:33792
	ds_read_b128 v[172:175], v221 offset:34816
	ds_read_b128 v[176:179], v221 offset:35840
	ds_read_b128 v[180:183], v221 offset:36864
	ds_read_b128 v[184:187], v221 offset:37888
	ds_read_b128 v[196:199], v221 offset:38912
	ds_read_b128 v[200:203], v221 offset:39936
	global_load_lds_dwordx4 v[212:213], off
	v_lshl_add_u64 v[212:213], s[16:17], 0, v[188:189]
	s_mov_b32 m0, s31
	s_nop 0
	global_load_lds_dwordx4 v[212:213], off
	s_waitcnt vmcnt(8)
	s_waitcnt lgkmcnt(0)
	s_barrier
	s_setprio 1
	s_waitcnt lgkmcnt(0)
	v_mfma_f32_16x16x32_bf16 v[136:139], v[124:127], v[164:167], v[136:139]
	v_mfma_f32_16x16x32_bf16 v[136:139], v[128:131], v[168:171], v[136:139]
	v_mfma_f32_16x16x32_bf16 v[120:123], v[148:151], v[164:167], v[120:123]
	v_mfma_f32_16x16x32_bf16 v[120:123], v[152:155], v[168:171], v[120:123]
	v_mfma_f32_16x16x32_bf16 v[132:135], v[140:143], v[164:167], v[132:135]
	v_mfma_f32_16x16x32_bf16 v[132:135], v[144:147], v[168:171], v[132:135]
	v_mfma_f32_16x16x32_bf16 v[116:119], v[156:159], v[164:167], v[116:119]
	v_mfma_f32_16x16x32_bf16 v[116:119], v[160:163], v[168:171], v[116:119]
	v_mfma_f32_16x16x32_bf16 v[112:115], v[124:127], v[172:175], v[112:115]
	v_mfma_f32_16x16x32_bf16 v[112:115], v[128:131], v[176:179], v[112:115]
	v_mfma_f32_16x16x32_bf16 v[104:107], v[148:151], v[172:175], v[104:107]
	v_mfma_f32_16x16x32_bf16 v[104:107], v[152:155], v[176:179], v[104:107]
	v_mfma_f32_16x16x32_bf16 v[108:111], v[140:143], v[172:175], v[108:111]
	v_mfma_f32_16x16x32_bf16 v[108:111], v[144:147], v[176:179], v[108:111]
	v_mfma_f32_16x16x32_bf16 v[100:103], v[156:159], v[172:175], v[100:103]
	v_mfma_f32_16x16x32_bf16 v[100:103], v[160:163], v[176:179], v[100:103]
	v_mfma_f32_16x16x32_bf16 v[96:99], v[124:127], v[180:183], v[96:99]
	v_mfma_f32_16x16x32_bf16 v[96:99], v[128:131], v[184:187], v[96:99]
	v_mfma_f32_16x16x32_bf16 v[88:91], v[148:151], v[180:183], v[88:91]
	v_mfma_f32_16x16x32_bf16 v[88:91], v[152:155], v[184:187], v[88:91]
	v_mfma_f32_16x16x32_bf16 v[92:95], v[140:143], v[180:183], v[92:95]
	v_mfma_f32_16x16x32_bf16 v[92:95], v[144:147], v[184:187], v[92:95]
	v_mfma_f32_16x16x32_bf16 v[84:87], v[156:159], v[180:183], v[84:87]
	v_mfma_f32_16x16x32_bf16 v[84:87], v[160:163], v[184:187], v[84:87]
	v_mfma_f32_16x16x32_bf16 v[80:83], v[124:127], v[196:199], v[80:83]
	v_mfma_f32_16x16x32_bf16 v[80:83], v[128:131], v[200:203], v[80:83]
	v_mfma_f32_16x16x32_bf16 v[72:75], v[148:151], v[196:199], v[72:75]
	v_mfma_f32_16x16x32_bf16 v[72:75], v[152:155], v[200:203], v[72:75]
	v_mfma_f32_16x16x32_bf16 v[76:79], v[140:143], v[196:199], v[76:79]
	v_mfma_f32_16x16x32_bf16 v[76:79], v[144:147], v[200:203], v[76:79]
	v_mfma_f32_16x16x32_bf16 v[68:71], v[156:159], v[196:199], v[68:71]
	v_mfma_f32_16x16x32_bf16 v[68:71], v[160:163], v[200:203], v[68:71]
	s_setprio 0
	s_barrier
	s_sleep 2
	s_add_i32 s16, s49, s2
	v_lshl_add_u64 v[204:205], v[204:205], 0, s[66:67]
	s_mov_b32 m0, s16
	ds_read_b128 v[164:167], v221 offset:49152
	ds_read_b128 v[168:171], v221 offset:50176
	ds_read_b128 v[172:175], v221 offset:51200
	ds_read_b128 v[176:179], v221 offset:52224
	ds_read_b128 v[180:183], v221 offset:53248
	ds_read_b128 v[184:187], v221 offset:54272
	ds_read_b128 v[196:199], v221 offset:55296
	ds_read_b128 v[200:203], v221 offset:56320
	global_load_lds_dwordx4 v[204:205], off
	s_add_i32 m0, s16, 0x2000
	s_add_u32 s16, s20, 0x160080
	v_lshl_add_u64 v[204:205], v[206:207], 0, s[66:67]
	s_addc_u32 s17, s21, 0
	s_add_i32 s20, s50, s2
	global_load_lds_dwordx4 v[204:205], off
	v_lshl_add_u64 v[204:205], s[16:17], 0, v[2:3]
	s_mov_b32 m0, s20
	s_nop 0
	global_load_lds_dwordx4 v[204:205], off
	v_lshl_add_u64 v[204:205], s[16:17], 0, v[190:191]
	s_add_i32 m0, s20, 0x2000
	s_nop 0
	global_load_lds_dwordx4 v[204:205], off
	v_lshl_add_u64 v[204:205], v[208:209], 0, s[66:67]
	s_mov_b32 m0, s34
	s_nop 0
	global_load_lds_dwordx4 v[204:205], off
	v_lshl_add_u64 v[204:205], v[210:211], 0, s[66:67]
	s_mov_b32 m0, s35
	s_nop 0
	global_load_lds_dwordx4 v[204:205], off
	s_waitcnt vmcnt(8)
	s_waitcnt lgkmcnt(0)
	s_barrier
	s_setprio 1
	s_waitcnt lgkmcnt(0)
	v_mfma_f32_16x16x32_bf16 v[64:67], v[124:127], v[164:167], v[64:67]
	v_mfma_f32_16x16x32_bf16 v[64:67], v[128:131], v[168:171], v[64:67]
	v_mfma_f32_16x16x32_bf16 v[56:59], v[148:151], v[164:167], v[56:59]
	v_mfma_f32_16x16x32_bf16 v[56:59], v[152:155], v[168:171], v[56:59]
	v_mfma_f32_16x16x32_bf16 v[60:63], v[140:143], v[164:167], v[60:63]
	v_mfma_f32_16x16x32_bf16 v[60:63], v[144:147], v[168:171], v[60:63]
	v_mfma_f32_16x16x32_bf16 v[52:55], v[156:159], v[164:167], v[52:55]
	v_mfma_f32_16x16x32_bf16 v[52:55], v[160:163], v[168:171], v[52:55]
	v_mfma_f32_16x16x32_bf16 v[48:51], v[124:127], v[172:175], v[48:51]
	v_mfma_f32_16x16x32_bf16 v[48:51], v[128:131], v[176:179], v[48:51]
	v_mfma_f32_16x16x32_bf16 v[40:43], v[148:151], v[172:175], v[40:43]
	v_mfma_f32_16x16x32_bf16 v[40:43], v[152:155], v[176:179], v[40:43]
	v_mfma_f32_16x16x32_bf16 v[44:47], v[140:143], v[172:175], v[44:47]
	v_mfma_f32_16x16x32_bf16 v[44:47], v[144:147], v[176:179], v[44:47]
	v_mfma_f32_16x16x32_bf16 v[36:39], v[156:159], v[172:175], v[36:39]
	v_mfma_f32_16x16x32_bf16 v[36:39], v[160:163], v[176:179], v[36:39]
	v_mfma_f32_16x16x32_bf16 v[32:35], v[124:127], v[180:183], v[32:35]
	v_mfma_f32_16x16x32_bf16 v[32:35], v[128:131], v[184:187], v[32:35]
	v_mfma_f32_16x16x32_bf16 v[24:27], v[148:151], v[180:183], v[24:27]
	v_mfma_f32_16x16x32_bf16 v[24:27], v[152:155], v[184:187], v[24:27]
	v_mfma_f32_16x16x32_bf16 v[28:31], v[140:143], v[180:183], v[28:31]
	v_mfma_f32_16x16x32_bf16 v[28:31], v[144:147], v[184:187], v[28:31]
	v_mfma_f32_16x16x32_bf16 v[20:23], v[156:159], v[180:183], v[20:23]
	v_mfma_f32_16x16x32_bf16 v[20:23], v[160:163], v[184:187], v[20:23]
	v_mfma_f32_16x16x32_bf16 v[16:19], v[124:127], v[196:199], v[16:19]
	v_mfma_f32_16x16x32_bf16 v[16:19], v[128:131], v[200:203], v[16:19]
	v_mfma_f32_16x16x32_bf16 v[8:11], v[148:151], v[196:199], v[8:11]
	v_mfma_f32_16x16x32_bf16 v[8:11], v[152:155], v[200:203], v[8:11]
	v_mfma_f32_16x16x32_bf16 v[12:15], v[140:143], v[196:199], v[12:15]
	v_mfma_f32_16x16x32_bf16 v[12:15], v[144:147], v[200:203], v[12:15]
	v_mfma_f32_16x16x32_bf16 v[4:7], v[156:159], v[196:199], v[4:7]
	v_mfma_f32_16x16x32_bf16 v[4:7], v[160:163], v[200:203], v[4:7]
	s_setprio 0
	s_barrier
	s_add_i32 s48, s48, 2
	s_add_u32 s40, s40, 0x100
	s_addc_u32 s41, s41, 0
	s_cmpk_gt_u32 s48, 0x55
	s_mov_b64 s[16:17], s[18:19]

.LBB0_346:
	s_add_u32 s38, s16, 0x100
	s_addc_u32 s39, s17, 0
	s_mov_b32 s43, -2
	s_sleep 2
	s_add_u32 s16, s14, 0x100
	s_addc_u32 s17, s15, 0
	s_add_i32 s44, 0, 0x10000
	s_cmpk_eq_i32 s43, 0x54
	s_cselect_b32 s21, s11, s17
	s_cselect_b32 s20, s10, s16
	s_cselect_b32 s19, s13, s39
	s_cselect_b32 s18, s12, s38
	s_add_i32 s45, 0, 0x14000
	v_add_u32_e32 v144, s44, v236
	v_add_u32_e32 v160, s45, v236
	ds_read_b128 v[132:135], v144
	ds_read_b128 v[136:139], v144 offset:1024
	ds_read_b128 v[140:143], v144 offset:2048
	ds_read_b128 v[144:147], v144 offset:3072
	ds_read_b128 v[148:151], v160
	ds_read_b128 v[152:155], v160 offset:1024
	ds_read_b128 v[156:159], v160 offset:2048
	ds_read_b128 v[160:163], v160 offset:3072
	v_lshl_add_u64 v[204:205], s[14:15], 0, v[200:201]
	s_add_i32 m0, s23, 0xc000
	ds_read_b128 v[164:167], v238
	ds_read_b128 v[168:171], v238 offset:1024
	ds_read_b128 v[172:175], v238 offset:2048
	ds_read_b128 v[176:179], v238 offset:3072
	ds_read_b128 v[180:183], v238 offset:4096
	ds_read_b128 v[184:187], v238 offset:5120
	ds_read_b128 v[188:191], v238 offset:6144
	ds_read_b128 v[192:195], v238 offset:7168
	global_load_lds_dwordx4 v[204:205], off
	v_lshl_add_u64 v[204:205], s[14:15], 0, v[202:203]
	s_add_i32 m0, s23, 0xe000
	s_nop 0
	global_load_lds_dwordx4 v[204:205], off
	s_waitcnt vmcnt(8)
	s_waitcnt lgkmcnt(0)
	s_barrier
	s_setprio 1
	s_waitcnt lgkmcnt(0)
	v_mfma_f32_16x16x32_bf16 v[128:131], v[132:135], v[164:167], 0
	v_mfma_f32_16x16x32_bf16 v[128:131], v[136:139], v[168:171], v[128:131]
	v_mfma_f32_16x16x32_bf16 v[120:123], v[148:151], v[164:167], 0
	v_mfma_f32_16x16x32_bf16 v[120:123], v[152:155], v[168:171], v[120:123]
	v_mfma_f32_16x16x32_bf16 v[124:127], v[140:143], v[164:167], 0
	v_mfma_f32_16x16x32_bf16 v[124:127], v[144:147], v[168:171], v[124:127]
	v_mfma_f32_16x16x32_bf16 v[112:115], v[156:159], v[164:167], 0
	v_mfma_f32_16x16x32_bf16 v[112:115], v[160:163], v[168:171], v[112:115]
	v_mfma_f32_16x16x32_bf16 v[116:119], v[132:135], v[172:175], 0
	v_mfma_f32_16x16x32_bf16 v[116:119], v[136:139], v[176:179], v[116:119]
	v_mfma_f32_16x16x32_bf16 v[104:107], v[148:151], v[172:175], 0
	v_mfma_f32_16x16x32_bf16 v[104:107], v[152:155], v[176:179], v[104:107]
	v_mfma_f32_16x16x32_bf16 v[108:111], v[140:143], v[172:175], 0
	v_mfma_f32_16x16x32_bf16 v[108:111], v[144:147], v[176:179], v[108:111]
	v_mfma_f32_16x16x32_bf16 v[96:99], v[156:159], v[172:175], 0
	v_mfma_f32_16x16x32_bf16 v[96:99], v[160:163], v[176:179], v[96:99]
	v_mfma_f32_16x16x32_bf16 v[100:103], v[132:135], v[180:183], 0
	v_mfma_f32_16x16x32_bf16 v[100:103], v[136:139], v[184:187], v[100:103]
	v_mfma_f32_16x16x32_bf16 v[88:91], v[148:151], v[180:183], 0
	v_mfma_f32_16x16x32_bf16 v[88:91], v[152:155], v[184:187], v[88:91]
	v_mfma_f32_16x16x32_bf16 v[92:95], v[140:143], v[180:183], 0
	v_mfma_f32_16x16x32_bf16 v[92:95], v[144:147], v[184:187], v[92:95]
	v_mfma_f32_16x16x32_bf16 v[80:83], v[156:159], v[180:183], 0
	v_mfma_f32_16x16x32_bf16 v[80:83], v[160:163], v[184:187], v[80:83]
	v_mfma_f32_16x16x32_bf16 v[84:87], v[132:135], v[188:191], 0
	v_mfma_f32_16x16x32_bf16 v[84:87], v[136:139], v[192:195], v[84:87]
	v_mfma_f32_16x16x32_bf16 v[72:75], v[148:151], v[188:191], 0
	v_mfma_f32_16x16x32_bf16 v[72:75], v[152:155], v[192:195], v[72:75]
	v_mfma_f32_16x16x32_bf16 v[76:79], v[140:143], v[188:191], 0
	v_mfma_f32_16x16x32_bf16 v[76:79], v[144:147], v[192:195], v[76:79]
	v_mfma_f32_16x16x32_bf16 v[68:71], v[156:159], v[188:191], 0
	v_mfma_f32_16x16x32_bf16 v[68:71], v[160:163], v[192:195], v[68:71]
	s_setprio 0
	s_barrier
	s_sleep 2
	s_add_i32 s14, s44, s22
	v_lshl_add_u64 v[204:205], s[18:19], 0, v[2:3]
	s_mov_b32 m0, s14
	ds_read_b128 v[164:167], v238 offset:16384
	ds_read_b128 v[168:171], v238 offset:17408
	ds_read_b128 v[172:175], v238 offset:18432
	ds_read_b128 v[176:179], v238 offset:19456
	ds_read_b128 v[180:183], v238 offset:20480
	ds_read_b128 v[184:187], v238 offset:21504
	ds_read_b128 v[188:191], v238 offset:22528
	ds_read_b128 v[192:195], v238 offset:23552
	global_load_lds_dwordx4 v[204:205], off
	s_add_i32 m0, s14, 0x2000
	s_add_u32 s14, s18, 0x160000
	v_lshl_add_u64 v[206:207], s[18:19], 0, v[198:199]
	s_addc_u32 s15, s19, 0
	s_add_i32 s44, s45, s22
	global_load_lds_dwordx4 v[206:207], off
	v_lshl_add_u64 v[208:209], s[14:15], 0, v[2:3]
	s_mov_b32 m0, s44
	v_lshl_add_u64 v[210:211], s[20:21], 0, v[196:197]
	global_load_lds_dwordx4 v[208:209], off
	v_lshl_add_u64 v[208:209], s[14:15], 0, v[198:199]
	s_add_i32 m0, s44, 0x2000
	s_nop 0
	global_load_lds_dwordx4 v[208:209], off
	v_lshl_add_u64 v[208:209], s[20:21], 0, v[0:1]
	s_mov_b32 m0, s23
	s_nop 0
	global_load_lds_dwordx4 v[208:209], off
	s_mov_b32 m0, s28
	s_nop 0
	global_load_lds_dwordx4 v[210:211], off
	s_waitcnt vmcnt(8)
	s_waitcnt lgkmcnt(0)
	s_barrier
	s_setprio 1
	s_waitcnt lgkmcnt(0)
	v_mfma_f32_16x16x32_bf16 v[64:67], v[132:135], v[164:167], 0
	v_mfma_f32_16x16x32_bf16 v[64:67], v[136:139], v[168:171], v[64:67]
	v_mfma_f32_16x16x32_bf16 v[56:59], v[148:151], v[164:167], 0
	v_mfma_f32_16x16x32_bf16 v[56:59], v[152:155], v[168:171], v[56:59]
	v_mfma_f32_16x16x32_bf16 v[60:63], v[140:143], v[164:167], 0
	v_mfma_f32_16x16x32_bf16 v[60:63], v[144:147], v[168:171], v[60:63]
	v_mfma_f32_16x16x32_bf16 v[48:51], v[156:159], v[164:167], 0
	v_mfma_f32_16x16x32_bf16 v[48:51], v[160:163], v[168:171], v[48:51]
	v_mfma_f32_16x16x32_bf16 v[52:55], v[132:135], v[172:175], 0
	v_mfma_f32_16x16x32_bf16 v[52:55], v[136:139], v[176:179], v[52:55]
	v_mfma_f32_16x16x32_bf16 v[40:43], v[148:151], v[172:175], 0
	v_mfma_f32_16x16x32_bf16 v[40:43], v[152:155], v[176:179], v[40:43]
	v_mfma_f32_16x16x32_bf16 v[44:47], v[140:143], v[172:175], 0
	v_mfma_f32_16x16x32_bf16 v[44:47], v[144:147], v[176:179], v[44:47]
	v_mfma_f32_16x16x32_bf16 v[32:35], v[156:159], v[172:175], 0
	v_mfma_f32_16x16x32_bf16 v[32:35], v[160:163], v[176:179], v[32:35]
	v_mfma_f32_16x16x32_bf16 v[36:39], v[132:135], v[180:183], 0
	v_mfma_f32_16x16x32_bf16 v[36:39], v[136:139], v[184:187], v[36:39]
	v_mfma_f32_16x16x32_bf16 v[24:27], v[148:151], v[180:183], 0
	v_mfma_f32_16x16x32_bf16 v[24:27], v[152:155], v[184:187], v[24:27]
	v_mfma_f32_16x16x32_bf16 v[28:31], v[140:143], v[180:183], 0
	v_mfma_f32_16x16x32_bf16 v[28:31], v[144:147], v[184:187], v[28:31]
	v_mfma_f32_16x16x32_bf16 v[16:19], v[156:159], v[180:183], 0
	v_mfma_f32_16x16x32_bf16 v[16:19], v[160:163], v[184:187], v[16:19]
	v_mfma_f32_16x16x32_bf16 v[20:23], v[132:135], v[188:191], 0
	v_mfma_f32_16x16x32_bf16 v[20:23], v[136:139], v[192:195], v[20:23]
	v_mfma_f32_16x16x32_bf16 v[8:11], v[148:151], v[188:191], 0
	v_mfma_f32_16x16x32_bf16 v[8:11], v[152:155], v[192:195], v[8:11]
	v_mfma_f32_16x16x32_bf16 v[12:15], v[140:143], v[188:191], 0
	v_mfma_f32_16x16x32_bf16 v[12:15], v[144:147], v[192:195], v[12:15]
	v_mfma_f32_16x16x32_bf16 v[4:7], v[156:159], v[188:191], 0
	v_mfma_f32_16x16x32_bf16 v[4:7], v[160:163], v[192:195], v[4:7]
	s_setprio 0
	s_barrier
	s_sleep 2
	s_add_i32 s44, 0, 0x18000
	s_add_i32 s45, 0, 0x1c000
	v_add_u32_e32 v144, s44, v236
	v_add_u32_e32 v160, s45, v236
	ds_read_b128 v[132:135], v144
	ds_read_b128 v[136:139], v144 offset:1024
	ds_read_b128 v[140:143], v144 offset:2048
	ds_read_b128 v[144:147], v144 offset:3072
	ds_read_b128 v[148:151], v160
	ds_read_b128 v[152:155], v160 offset:1024
	ds_read_b128 v[156:159], v160 offset:2048
	ds_read_b128 v[160:163], v160 offset:3072
	s_add_u32 s14, s20, 0x160000
	s_addc_u32 s15, s21, 0
	s_mov_b32 m0, s29
	v_lshl_add_u64 v[212:213], s[14:15], 0, v[0:1]
	ds_read_b128 v[164:167], v238 offset:32768
	ds_read_b128 v[168:171], v238 offset:33792
	ds_read_b128 v[172:175], v238 offset:34816
	ds_read_b128 v[176:179], v238 offset:35840
	ds_read_b128 v[180:183], v238 offset:36864
	ds_read_b128 v[184:187], v238 offset:37888
	ds_read_b128 v[188:191], v238 offset:38912
	ds_read_b128 v[192:195], v238 offset:39936
	global_load_lds_dwordx4 v[212:213], off
	v_lshl_add_u64 v[212:213], s[14:15], 0, v[196:197]
	s_mov_b32 m0, s30
	s_nop 0
	global_load_lds_dwordx4 v[212:213], off
	s_waitcnt vmcnt(8)
	s_waitcnt lgkmcnt(0)
	s_barrier
	s_setprio 1
	s_waitcnt lgkmcnt(0)
	v_mfma_f32_16x16x32_bf16 v[128:131], v[132:135], v[164:167], v[128:131]
	v_mfma_f32_16x16x32_bf16 v[128:131], v[136:139], v[168:171], v[128:131]
	v_mfma_f32_16x16x32_bf16 v[120:123], v[148:151], v[164:167], v[120:123]
	v_mfma_f32_16x16x32_bf16 v[120:123], v[152:155], v[168:171], v[120:123]
	v_mfma_f32_16x16x32_bf16 v[124:127], v[140:143], v[164:167], v[124:127]
	v_mfma_f32_16x16x32_bf16 v[124:127], v[144:147], v[168:171], v[124:127]
	v_mfma_f32_16x16x32_bf16 v[112:115], v[156:159], v[164:167], v[112:115]
	v_mfma_f32_16x16x32_bf16 v[112:115], v[160:163], v[168:171], v[112:115]
	v_mfma_f32_16x16x32_bf16 v[116:119], v[132:135], v[172:175], v[116:119]
	v_mfma_f32_16x16x32_bf16 v[116:119], v[136:139], v[176:179], v[116:119]
	v_mfma_f32_16x16x32_bf16 v[104:107], v[148:151], v[172:175], v[104:107]
	v_mfma_f32_16x16x32_bf16 v[104:107], v[152:155], v[176:179], v[104:107]
	v_mfma_f32_16x16x32_bf16 v[108:111], v[140:143], v[172:175], v[108:111]
	v_mfma_f32_16x16x32_bf16 v[108:111], v[144:147], v[176:179], v[108:111]
	v_mfma_f32_16x16x32_bf16 v[96:99], v[156:159], v[172:175], v[96:99]
	v_mfma_f32_16x16x32_bf16 v[96:99], v[160:163], v[176:179], v[96:99]
	v_mfma_f32_16x16x32_bf16 v[100:103], v[132:135], v[180:183], v[100:103]
	v_mfma_f32_16x16x32_bf16 v[100:103], v[136:139], v[184:187], v[100:103]
	v_mfma_f32_16x16x32_bf16 v[88:91], v[148:151], v[180:183], v[88:91]
	v_mfma_f32_16x16x32_bf16 v[88:91], v[152:155], v[184:187], v[88:91]
	v_mfma_f32_16x16x32_bf16 v[92:95], v[140:143], v[180:183], v[92:95]
	v_mfma_f32_16x16x32_bf16 v[92:95], v[144:147], v[184:187], v[92:95]
	v_mfma_f32_16x16x32_bf16 v[80:83], v[156:159], v[180:183], v[80:83]
	v_mfma_f32_16x16x32_bf16 v[80:83], v[160:163], v[184:187], v[80:83]
	v_mfma_f32_16x16x32_bf16 v[84:87], v[132:135], v[188:191], v[84:87]
	v_mfma_f32_16x16x32_bf16 v[84:87], v[136:139], v[192:195], v[84:87]
	v_mfma_f32_16x16x32_bf16 v[72:75], v[148:151], v[188:191], v[72:75]
	v_mfma_f32_16x16x32_bf16 v[72:75], v[152:155], v[192:195], v[72:75]
	v_mfma_f32_16x16x32_bf16 v[76:79], v[140:143], v[188:191], v[76:79]
	v_mfma_f32_16x16x32_bf16 v[76:79], v[144:147], v[192:195], v[76:79]
	v_mfma_f32_16x16x32_bf16 v[68:71], v[156:159], v[188:191], v[68:71]
	v_mfma_f32_16x16x32_bf16 v[68:71], v[160:163], v[192:195], v[68:71]
	s_setprio 0
	s_barrier
	s_sleep 2
	s_add_i32 s14, s44, s22
	v_lshl_add_u64 v[204:205], v[204:205], 0, s[66:67]
	s_mov_b32 m0, s14
	ds_read_b128 v[164:167], v238 offset:49152
	ds_read_b128 v[168:171], v238 offset:50176
	ds_read_b128 v[172:175], v238 offset:51200
	ds_read_b128 v[176:179], v238 offset:52224
	ds_read_b128 v[180:183], v238 offset:53248
	ds_read_b128 v[184:187], v238 offset:54272
	ds_read_b128 v[188:191], v238 offset:55296
	ds_read_b128 v[192:195], v238 offset:56320
	global_load_lds_dwordx4 v[204:205], off
	s_add_i32 m0, s14, 0x2000
	s_add_u32 s14, s18, 0x160080
	v_lshl_add_u64 v[204:205], v[206:207], 0, s[66:67]
	s_addc_u32 s15, s19, 0
	s_add_i32 s18, s45, s22
	global_load_lds_dwordx4 v[204:205], off
	v_lshl_add_u64 v[204:205], s[14:15], 0, v[2:3]
	s_mov_b32 m0, s18
	s_nop 0
	global_load_lds_dwordx4 v[204:205], off
	v_lshl_add_u64 v[204:205], s[14:15], 0, v[198:199]
	s_add_i32 m0, s18, 0x2000
	s_nop 0
	global_load_lds_dwordx4 v[204:205], off
	v_lshl_add_u64 v[204:205], v[208:209], 0, s[66:67]
	s_mov_b32 m0, s31
	s_nop 0
	global_load_lds_dwordx4 v[204:205], off
	v_lshl_add_u64 v[204:205], v[210:211], 0, s[66:67]
	s_mov_b32 m0, s34
	s_nop 0
	global_load_lds_dwordx4 v[204:205], off
	s_waitcnt vmcnt(8)
	s_waitcnt lgkmcnt(0)
	s_barrier
	s_setprio 1
	s_waitcnt lgkmcnt(0)
	v_mfma_f32_16x16x32_bf16 v[64:67], v[132:135], v[164:167], v[64:67]
	v_mfma_f32_16x16x32_bf16 v[64:67], v[136:139], v[168:171], v[64:67]
	v_mfma_f32_16x16x32_bf16 v[56:59], v[148:151], v[164:167], v[56:59]
	v_mfma_f32_16x16x32_bf16 v[56:59], v[152:155], v[168:171], v[56:59]
	v_mfma_f32_16x16x32_bf16 v[60:63], v[140:143], v[164:167], v[60:63]
	v_mfma_f32_16x16x32_bf16 v[60:63], v[144:147], v[168:171], v[60:63]
	v_mfma_f32_16x16x32_bf16 v[48:51], v[156:159], v[164:167], v[48:51]
	v_mfma_f32_16x16x32_bf16 v[48:51], v[160:163], v[168:171], v[48:51]
	v_mfma_f32_16x16x32_bf16 v[52:55], v[132:135], v[172:175], v[52:55]
	v_mfma_f32_16x16x32_bf16 v[52:55], v[136:139], v[176:179], v[52:55]
	v_mfma_f32_16x16x32_bf16 v[40:43], v[148:151], v[172:175], v[40:43]
	v_mfma_f32_16x16x32_bf16 v[40:43], v[152:155], v[176:179], v[40:43]
	v_mfma_f32_16x16x32_bf16 v[44:47], v[140:143], v[172:175], v[44:47]
	v_mfma_f32_16x16x32_bf16 v[44:47], v[144:147], v[176:179], v[44:47]
	v_mfma_f32_16x16x32_bf16 v[32:35], v[156:159], v[172:175], v[32:35]
	v_mfma_f32_16x16x32_bf16 v[32:35], v[160:163], v[176:179], v[32:35]
	v_mfma_f32_16x16x32_bf16 v[36:39], v[132:135], v[180:183], v[36:39]
	v_mfma_f32_16x16x32_bf16 v[36:39], v[136:139], v[184:187], v[36:39]
	v_mfma_f32_16x16x32_bf16 v[24:27], v[148:151], v[180:183], v[24:27]
	v_mfma_f32_16x16x32_bf16 v[24:27], v[152:155], v[184:187], v[24:27]
	v_mfma_f32_16x16x32_bf16 v[28:31], v[140:143], v[180:183], v[28:31]
	v_mfma_f32_16x16x32_bf16 v[28:31], v[144:147], v[184:187], v[28:31]
	v_mfma_f32_16x16x32_bf16 v[16:19], v[156:159], v[180:183], v[16:19]
	v_mfma_f32_16x16x32_bf16 v[16:19], v[160:163], v[184:187], v[16:19]
	v_mfma_f32_16x16x32_bf16 v[20:23], v[132:135], v[188:191], v[20:23]
	v_mfma_f32_16x16x32_bf16 v[20:23], v[136:139], v[192:195], v[20:23]
	v_mfma_f32_16x16x32_bf16 v[8:11], v[148:151], v[188:191], v[8:11]
	v_mfma_f32_16x16x32_bf16 v[8:11], v[152:155], v[192:195], v[8:11]
	v_mfma_f32_16x16x32_bf16 v[12:15], v[140:143], v[188:191], v[12:15]
	v_mfma_f32_16x16x32_bf16 v[12:15], v[144:147], v[192:195], v[12:15]
	v_mfma_f32_16x16x32_bf16 v[4:7], v[156:159], v[188:191], v[4:7]
	v_mfma_f32_16x16x32_bf16 v[4:7], v[160:163], v[192:195], v[4:7]
	s_setprio 0
	s_barrier
	s_add_i32 s43, s43, 2
	s_add_u32 s38, s38, 0x100
	s_addc_u32 s39, s39, 0
	s_cmpk_gt_u32 s43, 0x55
	s_mov_b64 s[14:15], s[16:17]

.LBB0_429:
	s_ashr_i32 s23, s22, 31
	s_lshl_b64 s[24:25], s[22:23], 20
	s_add_u32 s24, s51, s24
	s_addc_u32 s25, s52, s25
	s_and_b64 s[26:27], s[40:41], exec
	s_cselect_b32 s5, s25, s29
	s_cselect_b32 s23, s24, s28
	s_ashr_i32 s21, s20, 31
	s_lshl_b64 s[26:27], s[20:21], 20
	s_add_u32 s26, s12, s26
	s_addc_u32 s27, s13, s27
	s_and_b64 s[42:43], s[40:41], exec
	s_cselect_b32 s21, s27, s31
	s_cselect_b32 s62, s26, s30
	s_add_u32 s28, s28, 0x80080
	s_addc_u32 s29, s29, 0
	s_add_u32 s63, s30, 0x100
	s_addc_u32 s68, s31, 0
	s_mov_b32 s69, -2
	s_sleep 2
	s_add_u32 s30, s28, 0xfff80080
	s_addc_u32 s31, s29, -1
	s_add_i32 s70, 0, 0x10000
	s_cmp_eq_u32 s69, 28
	s_cselect_b32 s43, s5, s31
	s_cselect_b32 s42, s23, s30
	s_cselect_b32 s31, s21, s68
	s_cselect_b32 s30, s62, s63
	s_add_i32 s73, 0, 0x14000
	s_waitcnt lgkmcnt(0)
	v_add_u32_e32 v152, s70, v163
	v_add_u32_e32 v160, s73, v163
	ds_read_b128 v[132:135], v152
	ds_read_b128 v[136:139], v152 offset:1024
	ds_read_b128 v[148:151], v152 offset:2048
	ds_read_b128 v[152:155], v152 offset:3072
	ds_read_b128 v[156:159], v160
	ds_read_b128 v[170:173], v160 offset:1024
	ds_read_b128 v[174:177], v160 offset:2048
	ds_read_b128 v[178:181], v160 offset:3072
	v_lshl_add_u64 v[160:161], s[28:29], 0, v[144:145]
	s_add_i32 m0, s15, 0xc000
	ds_read_b128 v[182:185], v167
	ds_read_b128 v[186:189], v167 offset:1024
	ds_read_b128 v[190:193], v167 offset:2048
	ds_read_b128 v[194:197], v167 offset:3072
	ds_read_b128 v[198:201], v167 offset:4096
	ds_read_b128 v[208:211], v167 offset:5120
	ds_read_b128 v[212:215], v167 offset:6144
	ds_read_b128 v[216:219], v167 offset:7168
	global_load_lds_dwordx4 v[160:161], off
	v_lshl_add_u64 v[160:161], s[28:29], 0, v[146:147]
	s_add_i32 m0, s15, 0xe000
	s_nop 0
	global_load_lds_dwordx4 v[160:161], off
	s_waitcnt vmcnt(8)
	s_waitcnt lgkmcnt(0)
	s_barrier
	s_setprio 1
	s_waitcnt lgkmcnt(0)
	v_mfma_f32_16x16x32_bf16 v[128:131], v[132:135], v[182:185], 0
	v_mfma_f32_16x16x32_bf16 v[128:131], v[136:139], v[186:189], v[128:131]
	v_mfma_f32_16x16x32_bf16 v[116:119], v[156:159], v[182:185], 0
	v_mfma_f32_16x16x32_bf16 v[116:119], v[170:173], v[186:189], v[116:119]
	v_mfma_f32_16x16x32_bf16 v[124:127], v[148:151], v[182:185], 0
	v_mfma_f32_16x16x32_bf16 v[124:127], v[152:155], v[186:189], v[124:127]
	v_mfma_f32_16x16x32_bf16 v[108:111], v[174:177], v[182:185], 0
	v_mfma_f32_16x16x32_bf16 v[108:111], v[178:181], v[186:189], v[108:111]
	v_mfma_f32_16x16x32_bf16 v[120:123], v[132:135], v[190:193], 0
	v_mfma_f32_16x16x32_bf16 v[120:123], v[136:139], v[194:197], v[120:123]
	v_mfma_f32_16x16x32_bf16 v[100:103], v[156:159], v[190:193], 0
	v_mfma_f32_16x16x32_bf16 v[100:103], v[170:173], v[194:197], v[100:103]
	v_mfma_f32_16x16x32_bf16 v[112:115], v[148:151], v[190:193], 0
	v_mfma_f32_16x16x32_bf16 v[112:115], v[152:155], v[194:197], v[112:115]
	v_mfma_f32_16x16x32_bf16 v[92:95], v[174:177], v[190:193], 0
	v_mfma_f32_16x16x32_bf16 v[92:95], v[178:181], v[194:197], v[92:95]
	v_mfma_f32_16x16x32_bf16 v[104:107], v[132:135], v[198:201], 0
	v_mfma_f32_16x16x32_bf16 v[104:107], v[136:139], v[208:211], v[104:107]
	v_mfma_f32_16x16x32_bf16 v[84:87], v[156:159], v[198:201], 0
	v_mfma_f32_16x16x32_bf16 v[84:87], v[170:173], v[208:211], v[84:87]
	v_mfma_f32_16x16x32_bf16 v[96:99], v[148:151], v[198:201], 0
	v_mfma_f32_16x16x32_bf16 v[96:99], v[152:155], v[208:211], v[96:99]
	v_mfma_f32_16x16x32_bf16 v[76:79], v[174:177], v[198:201], 0
	v_mfma_f32_16x16x32_bf16 v[76:79], v[178:181], v[208:211], v[76:79]
	v_mfma_f32_16x16x32_bf16 v[88:91], v[132:135], v[212:215], 0
	v_mfma_f32_16x16x32_bf16 v[88:91], v[136:139], v[216:219], v[88:91]
	v_mfma_f32_16x16x32_bf16 v[72:75], v[156:159], v[212:215], 0
	v_mfma_f32_16x16x32_bf16 v[72:75], v[170:173], v[216:219], v[72:75]
	v_mfma_f32_16x16x32_bf16 v[80:83], v[148:151], v[212:215], 0
	v_mfma_f32_16x16x32_bf16 v[80:83], v[152:155], v[216:219], v[80:83]
	v_mfma_f32_16x16x32_bf16 v[68:71], v[174:177], v[212:215], 0
	v_mfma_f32_16x16x32_bf16 v[68:71], v[178:181], v[216:219], v[68:71]
	s_setprio 0
	s_barrier
	s_sleep 2
	s_add_i32 s70, s70, s0
	v_lshl_add_u64 v[160:161], s[30:31], 0, v[2:3]
	s_mov_b32 m0, s70
	ds_read_b128 v[182:185], v167 offset:16384
	ds_read_b128 v[186:189], v167 offset:17408
	ds_read_b128 v[190:193], v167 offset:18432
	ds_read_b128 v[194:197], v167 offset:19456
	ds_read_b128 v[198:201], v167 offset:20480
	ds_read_b128 v[208:211], v167 offset:21504
	ds_read_b128 v[212:215], v167 offset:22528
	ds_read_b128 v[216:219], v167 offset:23552
	global_load_lds_dwordx4 v[160:161], off
	s_add_i32 m0, s70, 0x2000
	s_add_u32 s70, s30, 0x80000
	v_lshl_add_u64 v[202:203], s[30:31], 0, v[142:143]
	s_addc_u32 s71, s31, 0
	s_add_i32 s73, s73, s0
	global_load_lds_dwordx4 v[202:203], off
	v_lshl_add_u64 v[204:205], s[70:71], 0, v[2:3]
	s_mov_b32 m0, s73
	v_lshl_add_u64 v[206:207], s[42:43], 0, v[140:141]
	global_load_lds_dwordx4 v[204:205], off
	v_lshl_add_u64 v[204:205], s[70:71], 0, v[142:143]
	s_add_i32 m0, s73, 0x2000
	s_nop 0
	global_load_lds_dwordx4 v[204:205], off
	v_lshl_add_u64 v[204:205], s[42:43], 0, v[0:1]
	s_mov_b32 m0, s15
	s_nop 0
	global_load_lds_dwordx4 v[204:205], off
	s_mov_b32 m0, s53
	s_nop 0
	global_load_lds_dwordx4 v[206:207], off
	s_waitcnt vmcnt(8)
	s_waitcnt lgkmcnt(0)
	s_barrier
	s_setprio 1
	s_waitcnt lgkmcnt(0)
	v_mfma_f32_16x16x32_bf16 v[64:67], v[132:135], v[182:185], 0
	v_mfma_f32_16x16x32_bf16 v[64:67], v[136:139], v[186:189], v[64:67]
	v_mfma_f32_16x16x32_bf16 v[52:55], v[156:159], v[182:185], 0
	v_mfma_f32_16x16x32_bf16 v[52:55], v[170:173], v[186:189], v[52:55]
	v_mfma_f32_16x16x32_bf16 v[60:63], v[148:151], v[182:185], 0
	v_mfma_f32_16x16x32_bf16 v[60:63], v[152:155], v[186:189], v[60:63]
	v_mfma_f32_16x16x32_bf16 v[44:47], v[174:177], v[182:185], 0
	v_mfma_f32_16x16x32_bf16 v[44:47], v[178:181], v[186:189], v[44:47]
	v_mfma_f32_16x16x32_bf16 v[56:59], v[132:135], v[190:193], 0
	v_mfma_f32_16x16x32_bf16 v[56:59], v[136:139], v[194:197], v[56:59]
	v_mfma_f32_16x16x32_bf16 v[36:39], v[156:159], v[190:193], 0
	v_mfma_f32_16x16x32_bf16 v[36:39], v[170:173], v[194:197], v[36:39]
	v_mfma_f32_16x16x32_bf16 v[48:51], v[148:151], v[190:193], 0
	v_mfma_f32_16x16x32_bf16 v[48:51], v[152:155], v[194:197], v[48:51]
	v_mfma_f32_16x16x32_bf16 v[28:31], v[174:177], v[190:193], 0
	v_mfma_f32_16x16x32_bf16 v[28:31], v[178:181], v[194:197], v[28:31]
	v_mfma_f32_16x16x32_bf16 v[40:43], v[132:135], v[198:201], 0
	v_mfma_f32_16x16x32_bf16 v[40:43], v[136:139], v[208:211], v[40:43]
	v_mfma_f32_16x16x32_bf16 v[20:23], v[156:159], v[198:201], 0
	v_mfma_f32_16x16x32_bf16 v[20:23], v[170:173], v[208:211], v[20:23]
	v_mfma_f32_16x16x32_bf16 v[32:35], v[148:151], v[198:201], 0
	v_mfma_f32_16x16x32_bf16 v[32:35], v[152:155], v[208:211], v[32:35]
	v_mfma_f32_16x16x32_bf16 v[12:15], v[174:177], v[198:201], 0
	v_mfma_f32_16x16x32_bf16 v[12:15], v[178:181], v[208:211], v[12:15]
	v_mfma_f32_16x16x32_bf16 v[24:27], v[132:135], v[212:215], 0
	v_mfma_f32_16x16x32_bf16 v[24:27], v[136:139], v[216:219], v[24:27]
	v_mfma_f32_16x16x32_bf16 v[8:11], v[156:159], v[212:215], 0
	v_mfma_f32_16x16x32_bf16 v[8:11], v[170:173], v[216:219], v[8:11]
	v_mfma_f32_16x16x32_bf16 v[16:19], v[148:151], v[212:215], 0
	v_mfma_f32_16x16x32_bf16 v[16:19], v[152:155], v[216:219], v[16:19]
	v_mfma_f32_16x16x32_bf16 v[4:7], v[174:177], v[212:215], 0
	v_mfma_f32_16x16x32_bf16 v[4:7], v[178:181], v[216:219], v[4:7]
	s_setprio 0
	s_barrier
	s_sleep 2
	s_add_i32 s70, 0, 0x18000
	s_add_i32 s71, 0, 0x1c000
	v_add_u32_e32 v152, s70, v163
	v_add_u32_e32 v178, s71, v163
	ds_read_b128 v[132:135], v152
	ds_read_b128 v[136:139], v152 offset:1024
	ds_read_b128 v[148:151], v152 offset:2048
	ds_read_b128 v[152:155], v152 offset:3072
	ds_read_b128 v[156:159], v178
	ds_read_b128 v[170:173], v178 offset:1024
	ds_read_b128 v[174:177], v178 offset:2048
	ds_read_b128 v[178:181], v178 offset:3072
	s_add_u32 s42, s42, 0x80000
	s_addc_u32 s43, s43, 0
	s_mov_b32 m0, s54
	v_lshl_add_u64 v[220:221], s[42:43], 0, v[0:1]
	ds_read_b128 v[182:185], v167 offset:32768
	ds_read_b128 v[186:189], v167 offset:33792
	ds_read_b128 v[190:193], v167 offset:34816
	ds_read_b128 v[194:197], v167 offset:35840
	ds_read_b128 v[198:201], v167 offset:36864
	ds_read_b128 v[208:211], v167 offset:37888
	ds_read_b128 v[212:215], v167 offset:38912
	ds_read_b128 v[216:219], v167 offset:39936
	global_load_lds_dwordx4 v[220:221], off
	v_lshl_add_u64 v[220:221], s[42:43], 0, v[140:141]
	s_mov_b32 m0, s55
	s_nop 0
	global_load_lds_dwordx4 v[220:221], off
	s_waitcnt vmcnt(8)
	s_waitcnt lgkmcnt(0)
	s_barrier
	s_setprio 1
	s_waitcnt lgkmcnt(0)
	v_mfma_f32_16x16x32_bf16 v[128:131], v[132:135], v[182:185], v[128:131]
	v_mfma_f32_16x16x32_bf16 v[128:131], v[136:139], v[186:189], v[128:131]
	v_mfma_f32_16x16x32_bf16 v[116:119], v[156:159], v[182:185], v[116:119]
	v_mfma_f32_16x16x32_bf16 v[116:119], v[170:173], v[186:189], v[116:119]
	v_mfma_f32_16x16x32_bf16 v[124:127], v[148:151], v[182:185], v[124:127]
	v_mfma_f32_16x16x32_bf16 v[124:127], v[152:155], v[186:189], v[124:127]
	v_mfma_f32_16x16x32_bf16 v[108:111], v[174:177], v[182:185], v[108:111]
	v_mfma_f32_16x16x32_bf16 v[108:111], v[178:181], v[186:189], v[108:111]
	v_mfma_f32_16x16x32_bf16 v[120:123], v[132:135], v[190:193], v[120:123]
	v_mfma_f32_16x16x32_bf16 v[120:123], v[136:139], v[194:197], v[120:123]
	v_mfma_f32_16x16x32_bf16 v[100:103], v[156:159], v[190:193], v[100:103]
	v_mfma_f32_16x16x32_bf16 v[100:103], v[170:173], v[194:197], v[100:103]
	v_mfma_f32_16x16x32_bf16 v[112:115], v[148:151], v[190:193], v[112:115]
	v_mfma_f32_16x16x32_bf16 v[112:115], v[152:155], v[194:197], v[112:115]
	v_mfma_f32_16x16x32_bf16 v[92:95], v[174:177], v[190:193], v[92:95]
	v_mfma_f32_16x16x32_bf16 v[92:95], v[178:181], v[194:197], v[92:95]
	v_mfma_f32_16x16x32_bf16 v[104:107], v[132:135], v[198:201], v[104:107]
	v_mfma_f32_16x16x32_bf16 v[104:107], v[136:139], v[208:211], v[104:107]
	v_mfma_f32_16x16x32_bf16 v[84:87], v[156:159], v[198:201], v[84:87]
	v_mfma_f32_16x16x32_bf16 v[84:87], v[170:173], v[208:211], v[84:87]
	v_mfma_f32_16x16x32_bf16 v[96:99], v[148:151], v[198:201], v[96:99]
	v_mfma_f32_16x16x32_bf16 v[96:99], v[152:155], v[208:211], v[96:99]
	v_mfma_f32_16x16x32_bf16 v[76:79], v[174:177], v[198:201], v[76:79]
	v_mfma_f32_16x16x32_bf16 v[76:79], v[178:181], v[208:211], v[76:79]
	v_mfma_f32_16x16x32_bf16 v[88:91], v[132:135], v[212:215], v[88:91]
	v_mfma_f32_16x16x32_bf16 v[88:91], v[136:139], v[216:219], v[88:91]
	v_mfma_f32_16x16x32_bf16 v[72:75], v[156:159], v[212:215], v[72:75]
	v_mfma_f32_16x16x32_bf16 v[72:75], v[170:173], v[216:219], v[72:75]
	v_mfma_f32_16x16x32_bf16 v[80:83], v[148:151], v[212:215], v[80:83]
	v_mfma_f32_16x16x32_bf16 v[80:83], v[152:155], v[216:219], v[80:83]
	v_mfma_f32_16x16x32_bf16 v[68:71], v[174:177], v[212:215], v[68:71]
	v_mfma_f32_16x16x32_bf16 v[68:71], v[178:181], v[216:219], v[68:71]
	s_setprio 0
	s_barrier
	s_sleep 2
	s_add_i32 s42, s70, s0
	v_lshl_add_u64 v[160:161], v[160:161], 0, s[66:67]
	s_mov_b32 m0, s42
	ds_read_b128 v[182:185], v167 offset:49152
	ds_read_b128 v[186:189], v167 offset:50176
	ds_read_b128 v[190:193], v167 offset:51200
	ds_read_b128 v[194:197], v167 offset:52224
	ds_read_b128 v[198:201], v167 offset:53248
	ds_read_b128 v[208:211], v167 offset:54272
	ds_read_b128 v[212:215], v167 offset:55296
	ds_read_b128 v[216:219], v167 offset:56320
	global_load_lds_dwordx4 v[160:161], off
	s_add_i32 m0, s42, 0x2000
	s_add_u32 s30, s30, 0x80080
	v_lshl_add_u64 v[160:161], v[202:203], 0, s[66:67]
	s_addc_u32 s31, s31, 0
	s_add_i32 s42, s71, s0
	global_load_lds_dwordx4 v[160:161], off
	v_lshl_add_u64 v[160:161], s[30:31], 0, v[2:3]
	s_mov_b32 m0, s42
	s_nop 0
	global_load_lds_dwordx4 v[160:161], off
	v_lshl_add_u64 v[160:161], s[30:31], 0, v[142:143]
	s_add_i32 m0, s42, 0x2000
	s_nop 0
	global_load_lds_dwordx4 v[160:161], off
	v_lshl_add_u64 v[160:161], v[204:205], 0, s[66:67]
	s_mov_b32 m0, s60
	s_nop 0
	global_load_lds_dwordx4 v[160:161], off
	v_lshl_add_u64 v[160:161], v[206:207], 0, s[66:67]
	s_mov_b32 m0, s64
	s_nop 0
	global_load_lds_dwordx4 v[160:161], off
	s_waitcnt vmcnt(8)
	s_waitcnt lgkmcnt(0)
	s_barrier
	s_setprio 1
	s_waitcnt lgkmcnt(0)
	v_mfma_f32_16x16x32_bf16 v[64:67], v[132:135], v[182:185], v[64:67]
	v_mfma_f32_16x16x32_bf16 v[64:67], v[136:139], v[186:189], v[64:67]
	v_mfma_f32_16x16x32_bf16 v[52:55], v[156:159], v[182:185], v[52:55]
	v_mfma_f32_16x16x32_bf16 v[52:55], v[170:173], v[186:189], v[52:55]
	v_mfma_f32_16x16x32_bf16 v[60:63], v[148:151], v[182:185], v[60:63]
	v_mfma_f32_16x16x32_bf16 v[60:63], v[152:155], v[186:189], v[60:63]
	v_mfma_f32_16x16x32_bf16 v[44:47], v[174:177], v[182:185], v[44:47]
	v_mfma_f32_16x16x32_bf16 v[44:47], v[178:181], v[186:189], v[44:47]
	v_mfma_f32_16x16x32_bf16 v[56:59], v[132:135], v[190:193], v[56:59]
	v_mfma_f32_16x16x32_bf16 v[56:59], v[136:139], v[194:197], v[56:59]
	v_mfma_f32_16x16x32_bf16 v[36:39], v[156:159], v[190:193], v[36:39]
	v_mfma_f32_16x16x32_bf16 v[36:39], v[170:173], v[194:197], v[36:39]
	v_mfma_f32_16x16x32_bf16 v[48:51], v[148:151], v[190:193], v[48:51]
	v_mfma_f32_16x16x32_bf16 v[48:51], v[152:155], v[194:197], v[48:51]
	v_mfma_f32_16x16x32_bf16 v[28:31], v[174:177], v[190:193], v[28:31]
	v_mfma_f32_16x16x32_bf16 v[28:31], v[178:181], v[194:197], v[28:31]
	v_mfma_f32_16x16x32_bf16 v[40:43], v[132:135], v[198:201], v[40:43]
	v_mfma_f32_16x16x32_bf16 v[40:43], v[136:139], v[208:211], v[40:43]
	v_mfma_f32_16x16x32_bf16 v[20:23], v[156:159], v[198:201], v[20:23]
	v_mfma_f32_16x16x32_bf16 v[20:23], v[170:173], v[208:211], v[20:23]
	v_mfma_f32_16x16x32_bf16 v[32:35], v[148:151], v[198:201], v[32:35]
	v_mfma_f32_16x16x32_bf16 v[32:35], v[152:155], v[208:211], v[32:35]
	v_mfma_f32_16x16x32_bf16 v[12:15], v[174:177], v[198:201], v[12:15]
	v_mfma_f32_16x16x32_bf16 v[12:15], v[178:181], v[208:211], v[12:15]
	v_mfma_f32_16x16x32_bf16 v[24:27], v[132:135], v[212:215], v[24:27]
	v_mfma_f32_16x16x32_bf16 v[24:27], v[136:139], v[216:219], v[24:27]
	v_mfma_f32_16x16x32_bf16 v[8:11], v[156:159], v[212:215], v[8:11]
	v_mfma_f32_16x16x32_bf16 v[8:11], v[170:173], v[216:219], v[8:11]
	v_mfma_f32_16x16x32_bf16 v[16:19], v[148:151], v[212:215], v[16:19]
	v_mfma_f32_16x16x32_bf16 v[16:19], v[152:155], v[216:219], v[16:19]
	v_mfma_f32_16x16x32_bf16 v[4:7], v[174:177], v[212:215], v[4:7]
	v_mfma_f32_16x16x32_bf16 v[4:7], v[178:181], v[216:219], v[4:7]
	s_setprio 0
	s_barrier
	s_add_i32 s69, s69, 2
	s_add_u32 s28, s28, 0x100
	s_addc_u32 s29, s29, 0
	s_add_u32 s63, s63, 0x100
	s_addc_u32 s68, s68, 0
	s_cmp_gt_u32 s69, 29

.LBB0_494:
	s_ashr_i32 s15, s14, 31
	s_lshl_b64 s[16:17], s[14:15], 20
	s_add_u32 s16, s27, s16
	s_addc_u32 s17, s28, s17
	s_and_b64 s[18:19], s[38:39], exec
	s_cselect_b32 s15, s17, s21
	s_cselect_b32 s43, s16, s20
	s_ashr_i32 s11, s10, 31
	s_lshl_b64 s[18:19], s[10:11], 20
	s_add_u32 s18, s29, s18
	s_addc_u32 s19, s30, s19
	s_and_b64 s[24:25], s[38:39], exec
	s_cselect_b32 s11, s19, s23
	s_cselect_b32 s44, s18, s22
	s_add_u32 s20, s20, 0x80080
	s_addc_u32 s21, s21, 0
	s_add_u32 s45, s22, 0x100
	s_addc_u32 s46, s23, 0
	s_mov_b32 s47, -2
	s_sleep 2
	s_add_u32 s22, s20, 0xfff80080
	s_addc_u32 s23, s21, -1
	s_add_i32 s48, 0, 0x10000
	s_cmp_eq_u32 s47, 28
	s_cselect_b32 s25, s15, s23
	s_cselect_b32 s24, s43, s22
	s_cselect_b32 s23, s11, s46
	s_cselect_b32 s22, s44, s45
	s_add_i32 s50, 0, 0x14000
	s_waitcnt lgkmcnt(0)
	v_add_u32_e32 v152, s48, v137
	v_add_u32_e32 v168, s50, v137
	ds_read_b128 v[140:143], v152
	ds_read_b128 v[144:147], v152 offset:1024
	ds_read_b128 v[148:151], v152 offset:2048
	ds_read_b128 v[152:155], v152 offset:3072
	ds_read_b128 v[156:159], v168
	ds_read_b128 v[160:163], v168 offset:1024
	ds_read_b128 v[164:167], v168 offset:2048
	ds_read_b128 v[168:171], v168 offset:3072
	v_lshl_add_u64 v[204:205], s[20:21], 0, v[132:133]
	s_add_i32 m0, s31, 0xc000
	ds_read_b128 v[172:175], v139
	ds_read_b128 v[176:179], v139 offset:1024
	ds_read_b128 v[180:183], v139 offset:2048
	ds_read_b128 v[184:187], v139 offset:3072
	ds_read_b128 v[188:191], v139 offset:4096
	ds_read_b128 v[192:195], v139 offset:5120
	ds_read_b128 v[196:199], v139 offset:6144
	ds_read_b128 v[200:203], v139 offset:7168
	global_load_lds_dwordx4 v[204:205], off
	v_lshl_add_u64 v[204:205], s[20:21], 0, v[134:135]
	s_add_i32 m0, s31, 0xe000
	s_nop 0
	global_load_lds_dwordx4 v[204:205], off
	s_waitcnt vmcnt(8)
	s_waitcnt lgkmcnt(0)
	s_barrier
	s_setprio 1
	s_waitcnt lgkmcnt(0)
	v_mfma_f32_16x16x32_bf16 v[128:131], v[140:143], v[172:175], 0
	v_mfma_f32_16x16x32_bf16 v[128:131], v[144:147], v[176:179], v[128:131]
	v_mfma_f32_16x16x32_bf16 v[112:115], v[156:159], v[172:175], 0
	v_mfma_f32_16x16x32_bf16 v[112:115], v[160:163], v[176:179], v[112:115]
	v_mfma_f32_16x16x32_bf16 v[124:127], v[148:151], v[172:175], 0
	v_mfma_f32_16x16x32_bf16 v[124:127], v[152:155], v[176:179], v[124:127]
	v_mfma_f32_16x16x32_bf16 v[104:107], v[164:167], v[172:175], 0
	v_mfma_f32_16x16x32_bf16 v[104:107], v[168:171], v[176:179], v[104:107]
	v_mfma_f32_16x16x32_bf16 v[120:123], v[140:143], v[180:183], 0
	v_mfma_f32_16x16x32_bf16 v[120:123], v[144:147], v[184:187], v[120:123]
	v_mfma_f32_16x16x32_bf16 v[96:99], v[156:159], v[180:183], 0
	v_mfma_f32_16x16x32_bf16 v[96:99], v[160:163], v[184:187], v[96:99]
	v_mfma_f32_16x16x32_bf16 v[116:119], v[148:151], v[180:183], 0
	v_mfma_f32_16x16x32_bf16 v[116:119], v[152:155], v[184:187], v[116:119]
	v_mfma_f32_16x16x32_bf16 v[88:91], v[164:167], v[180:183], 0
	v_mfma_f32_16x16x32_bf16 v[88:91], v[168:171], v[184:187], v[88:91]
	v_mfma_f32_16x16x32_bf16 v[108:111], v[140:143], v[188:191], 0
	v_mfma_f32_16x16x32_bf16 v[108:111], v[144:147], v[192:195], v[108:111]
	v_mfma_f32_16x16x32_bf16 v[80:83], v[156:159], v[188:191], 0
	v_mfma_f32_16x16x32_bf16 v[80:83], v[160:163], v[192:195], v[80:83]
	v_mfma_f32_16x16x32_bf16 v[100:103], v[148:151], v[188:191], 0
	v_mfma_f32_16x16x32_bf16 v[100:103], v[152:155], v[192:195], v[100:103]
	v_mfma_f32_16x16x32_bf16 v[76:79], v[164:167], v[188:191], 0
	v_mfma_f32_16x16x32_bf16 v[76:79], v[168:171], v[192:195], v[76:79]
	v_mfma_f32_16x16x32_bf16 v[92:95], v[140:143], v[196:199], 0
	v_mfma_f32_16x16x32_bf16 v[92:95], v[144:147], v[200:203], v[92:95]
	v_mfma_f32_16x16x32_bf16 v[72:75], v[156:159], v[196:199], 0
	v_mfma_f32_16x16x32_bf16 v[72:75], v[160:163], v[200:203], v[72:75]
	v_mfma_f32_16x16x32_bf16 v[84:87], v[148:151], v[196:199], 0
	v_mfma_f32_16x16x32_bf16 v[84:87], v[152:155], v[200:203], v[84:87]
	v_mfma_f32_16x16x32_bf16 v[68:71], v[164:167], v[196:199], 0
	v_mfma_f32_16x16x32_bf16 v[68:71], v[168:171], v[200:203], v[68:71]
	s_setprio 0
	s_barrier
	s_sleep 2
	s_add_i32 s48, s48, s0
	v_lshl_add_u64 v[204:205], s[22:23], 0, v[2:3]
	s_mov_b32 m0, s48
	ds_read_b128 v[172:175], v139 offset:16384
	ds_read_b128 v[176:179], v139 offset:17408
	ds_read_b128 v[180:183], v139 offset:18432
	ds_read_b128 v[184:187], v139 offset:19456
	ds_read_b128 v[188:191], v139 offset:20480
	ds_read_b128 v[192:195], v139 offset:21504
	ds_read_b128 v[196:199], v139 offset:22528
	ds_read_b128 v[200:203], v139 offset:23552
	global_load_lds_dwordx4 v[204:205], off
	s_add_i32 m0, s48, 0x2000
	s_add_u32 s48, s22, 0x80000
	v_lshl_add_u64 v[206:207], s[22:23], 0, v[0:1]
	s_addc_u32 s49, s23, 0
	s_add_i32 s50, s50, s0
	global_load_lds_dwordx4 v[206:207], off
	v_lshl_add_u64 v[208:209], s[48:49], 0, v[2:3]
	s_mov_b32 m0, s50
	v_lshl_add_u64 v[210:211], s[24:25], 0, v[0:1]
	global_load_lds_dwordx4 v[208:209], off
	v_lshl_add_u64 v[208:209], s[48:49], 0, v[0:1]
	s_add_i32 m0, s50, 0x2000
	s_nop 0
	global_load_lds_dwordx4 v[208:209], off
	v_lshl_add_u64 v[208:209], s[24:25], 0, v[2:3]
	s_mov_b32 m0, s31
	s_nop 0
	global_load_lds_dwordx4 v[208:209], off
	s_mov_b32 m0, s40
	s_nop 0
	global_load_lds_dwordx4 v[210:211], off
	s_waitcnt vmcnt(8)
	s_waitcnt lgkmcnt(0)
	s_barrier
	s_setprio 1
	s_waitcnt lgkmcnt(0)
	v_mfma_f32_16x16x32_bf16 v[64:67], v[140:143], v[172:175], 0
	v_mfma_f32_16x16x32_bf16 v[64:67], v[144:147], v[176:179], v[64:67]
	v_mfma_f32_16x16x32_bf16 v[48:51], v[156:159], v[172:175], 0
	v_mfma_f32_16x16x32_bf16 v[48:51], v[160:163], v[176:179], v[48:51]
	v_mfma_f32_16x16x32_bf16 v[60:63], v[148:151], v[172:175], 0
	v_mfma_f32_16x16x32_bf16 v[60:63], v[152:155], v[176:179], v[60:63]
	v_mfma_f32_16x16x32_bf16 v[44:47], v[164:167], v[172:175], 0
	v_mfma_f32_16x16x32_bf16 v[44:47], v[168:171], v[176:179], v[44:47]
	v_mfma_f32_16x16x32_bf16 v[56:59], v[140:143], v[180:183], 0
	v_mfma_f32_16x16x32_bf16 v[56:59], v[144:147], v[184:187], v[56:59]
	v_mfma_f32_16x16x32_bf16 v[32:35], v[156:159], v[180:183], 0
	v_mfma_f32_16x16x32_bf16 v[32:35], v[160:163], v[184:187], v[32:35]
	v_mfma_f32_16x16x32_bf16 v[52:55], v[148:151], v[180:183], 0
	v_mfma_f32_16x16x32_bf16 v[52:55], v[152:155], v[184:187], v[52:55]
	v_mfma_f32_16x16x32_bf16 v[28:31], v[164:167], v[180:183], 0
	v_mfma_f32_16x16x32_bf16 v[28:31], v[168:171], v[184:187], v[28:31]
	v_mfma_f32_16x16x32_bf16 v[40:43], v[140:143], v[188:191], 0
	v_mfma_f32_16x16x32_bf16 v[40:43], v[144:147], v[192:195], v[40:43]
	v_mfma_f32_16x16x32_bf16 v[16:19], v[156:159], v[188:191], 0
	v_mfma_f32_16x16x32_bf16 v[16:19], v[160:163], v[192:195], v[16:19]
	v_mfma_f32_16x16x32_bf16 v[36:39], v[148:151], v[188:191], 0
	v_mfma_f32_16x16x32_bf16 v[36:39], v[152:155], v[192:195], v[36:39]
	v_mfma_f32_16x16x32_bf16 v[12:15], v[164:167], v[188:191], 0
	v_mfma_f32_16x16x32_bf16 v[12:15], v[168:171], v[192:195], v[12:15]
	v_mfma_f32_16x16x32_bf16 v[24:27], v[140:143], v[196:199], 0
	v_mfma_f32_16x16x32_bf16 v[24:27], v[144:147], v[200:203], v[24:27]
	v_mfma_f32_16x16x32_bf16 v[8:11], v[156:159], v[196:199], 0
	v_mfma_f32_16x16x32_bf16 v[8:11], v[160:163], v[200:203], v[8:11]
	v_mfma_f32_16x16x32_bf16 v[20:23], v[148:151], v[196:199], 0
	v_mfma_f32_16x16x32_bf16 v[20:23], v[152:155], v[200:203], v[20:23]
	v_mfma_f32_16x16x32_bf16 v[4:7], v[164:167], v[196:199], 0
	v_mfma_f32_16x16x32_bf16 v[4:7], v[168:171], v[200:203], v[4:7]
	s_setprio 0
	s_barrier
	s_sleep 2
	s_add_i32 s48, 0, 0x18000
	s_add_i32 s49, 0, 0x1c000
	v_add_u32_e32 v152, s48, v137
	v_add_u32_e32 v168, s49, v137
	ds_read_b128 v[140:143], v152
	ds_read_b128 v[144:147], v152 offset:1024
	ds_read_b128 v[148:151], v152 offset:2048
	ds_read_b128 v[152:155], v152 offset:3072
	ds_read_b128 v[156:159], v168
	ds_read_b128 v[160:163], v168 offset:1024
	ds_read_b128 v[164:167], v168 offset:2048
	ds_read_b128 v[168:171], v168 offset:3072
	s_add_u32 s24, s24, 0x80000
	s_addc_u32 s25, s25, 0
	s_mov_b32 m0, s41
	v_lshl_add_u64 v[212:213], s[24:25], 0, v[2:3]
	ds_read_b128 v[172:175], v139 offset:32768
	ds_read_b128 v[176:179], v139 offset:33792
	ds_read_b128 v[180:183], v139 offset:34816
	ds_read_b128 v[184:187], v139 offset:35840
	ds_read_b128 v[188:191], v139 offset:36864
	ds_read_b128 v[192:195], v139 offset:37888
	ds_read_b128 v[196:199], v139 offset:38912
	ds_read_b128 v[200:203], v139 offset:39936
	global_load_lds_dwordx4 v[212:213], off
	v_lshl_add_u64 v[212:213], s[24:25], 0, v[0:1]
	s_mov_b32 m0, s42
	s_nop 0
	global_load_lds_dwordx4 v[212:213], off
	s_waitcnt vmcnt(8)
	s_waitcnt lgkmcnt(0)
	s_barrier
	s_setprio 1
	s_waitcnt lgkmcnt(0)
	v_mfma_f32_16x16x32_bf16 v[128:131], v[140:143], v[172:175], v[128:131]
	v_mfma_f32_16x16x32_bf16 v[128:131], v[144:147], v[176:179], v[128:131]
	v_mfma_f32_16x16x32_bf16 v[112:115], v[156:159], v[172:175], v[112:115]
	v_mfma_f32_16x16x32_bf16 v[112:115], v[160:163], v[176:179], v[112:115]
	v_mfma_f32_16x16x32_bf16 v[124:127], v[148:151], v[172:175], v[124:127]
	v_mfma_f32_16x16x32_bf16 v[124:127], v[152:155], v[176:179], v[124:127]
	v_mfma_f32_16x16x32_bf16 v[104:107], v[164:167], v[172:175], v[104:107]
	v_mfma_f32_16x16x32_bf16 v[104:107], v[168:171], v[176:179], v[104:107]
	v_mfma_f32_16x16x32_bf16 v[120:123], v[140:143], v[180:183], v[120:123]
	v_mfma_f32_16x16x32_bf16 v[120:123], v[144:147], v[184:187], v[120:123]
	v_mfma_f32_16x16x32_bf16 v[96:99], v[156:159], v[180:183], v[96:99]
	v_mfma_f32_16x16x32_bf16 v[96:99], v[160:163], v[184:187], v[96:99]
	v_mfma_f32_16x16x32_bf16 v[116:119], v[148:151], v[180:183], v[116:119]
	v_mfma_f32_16x16x32_bf16 v[116:119], v[152:155], v[184:187], v[116:119]
	v_mfma_f32_16x16x32_bf16 v[88:91], v[164:167], v[180:183], v[88:91]
	v_mfma_f32_16x16x32_bf16 v[88:91], v[168:171], v[184:187], v[88:91]
	v_mfma_f32_16x16x32_bf16 v[108:111], v[140:143], v[188:191], v[108:111]
	v_mfma_f32_16x16x32_bf16 v[108:111], v[144:147], v[192:195], v[108:111]
	v_mfma_f32_16x16x32_bf16 v[80:83], v[156:159], v[188:191], v[80:83]
	v_mfma_f32_16x16x32_bf16 v[80:83], v[160:163], v[192:195], v[80:83]
	v_mfma_f32_16x16x32_bf16 v[100:103], v[148:151], v[188:191], v[100:103]
	v_mfma_f32_16x16x32_bf16 v[100:103], v[152:155], v[192:195], v[100:103]
	v_mfma_f32_16x16x32_bf16 v[76:79], v[164:167], v[188:191], v[76:79]
	v_mfma_f32_16x16x32_bf16 v[76:79], v[168:171], v[192:195], v[76:79]
	v_mfma_f32_16x16x32_bf16 v[92:95], v[140:143], v[196:199], v[92:95]
	v_mfma_f32_16x16x32_bf16 v[92:95], v[144:147], v[200:203], v[92:95]
	v_mfma_f32_16x16x32_bf16 v[72:75], v[156:159], v[196:199], v[72:75]
	v_mfma_f32_16x16x32_bf16 v[72:75], v[160:163], v[200:203], v[72:75]
	v_mfma_f32_16x16x32_bf16 v[84:87], v[148:151], v[196:199], v[84:87]
	v_mfma_f32_16x16x32_bf16 v[84:87], v[152:155], v[200:203], v[84:87]
	v_mfma_f32_16x16x32_bf16 v[68:71], v[164:167], v[196:199], v[68:71]
	v_mfma_f32_16x16x32_bf16 v[68:71], v[168:171], v[200:203], v[68:71]
	s_setprio 0
	s_barrier
	s_sleep 2
	s_add_i32 s24, s48, s0
	v_lshl_add_u64 v[204:205], v[204:205], 0, s[66:67]
	s_mov_b32 m0, s24
	ds_read_b128 v[172:175], v139 offset:49152
	ds_read_b128 v[176:179], v139 offset:50176
	ds_read_b128 v[180:183], v139 offset:51200
	ds_read_b128 v[184:187], v139 offset:52224
	ds_read_b128 v[188:191], v139 offset:53248
	ds_read_b128 v[192:195], v139 offset:54272
	ds_read_b128 v[196:199], v139 offset:55296
	ds_read_b128 v[200:203], v139 offset:56320
	global_load_lds_dwordx4 v[204:205], off
	s_add_i32 m0, s24, 0x2000
	s_add_u32 s22, s22, 0x80080
	v_lshl_add_u64 v[204:205], v[206:207], 0, s[66:67]
	s_addc_u32 s23, s23, 0
	s_add_i32 s24, s49, s0
	global_load_lds_dwordx4 v[204:205], off
	v_lshl_add_u64 v[204:205], s[22:23], 0, v[2:3]
	s_mov_b32 m0, s24
	s_nop 0
	global_load_lds_dwordx4 v[204:205], off
	v_lshl_add_u64 v[204:205], s[22:23], 0, v[0:1]
	s_add_i32 m0, s24, 0x2000
	s_nop 0
	global_load_lds_dwordx4 v[204:205], off
	v_lshl_add_u64 v[204:205], v[208:209], 0, s[66:67]
	s_mov_b32 m0, s1
	s_nop 0
	global_load_lds_dwordx4 v[204:205], off
	v_lshl_add_u64 v[204:205], v[210:211], 0, s[66:67]
	s_mov_b32 m0, s34
	s_nop 0
	global_load_lds_dwordx4 v[204:205], off
	s_waitcnt vmcnt(8)
	s_waitcnt lgkmcnt(0)
	s_barrier
	s_setprio 1
	s_waitcnt lgkmcnt(0)
	v_mfma_f32_16x16x32_bf16 v[64:67], v[140:143], v[172:175], v[64:67]
	v_mfma_f32_16x16x32_bf16 v[64:67], v[144:147], v[176:179], v[64:67]
	v_mfma_f32_16x16x32_bf16 v[48:51], v[156:159], v[172:175], v[48:51]
	v_mfma_f32_16x16x32_bf16 v[48:51], v[160:163], v[176:179], v[48:51]
	v_mfma_f32_16x16x32_bf16 v[60:63], v[148:151], v[172:175], v[60:63]
	v_mfma_f32_16x16x32_bf16 v[60:63], v[152:155], v[176:179], v[60:63]
	v_mfma_f32_16x16x32_bf16 v[44:47], v[164:167], v[172:175], v[44:47]
	v_mfma_f32_16x16x32_bf16 v[44:47], v[168:171], v[176:179], v[44:47]
	v_mfma_f32_16x16x32_bf16 v[56:59], v[140:143], v[180:183], v[56:59]
	v_mfma_f32_16x16x32_bf16 v[56:59], v[144:147], v[184:187], v[56:59]
	v_mfma_f32_16x16x32_bf16 v[32:35], v[156:159], v[180:183], v[32:35]
	v_mfma_f32_16x16x32_bf16 v[32:35], v[160:163], v[184:187], v[32:35]
	v_mfma_f32_16x16x32_bf16 v[52:55], v[148:151], v[180:183], v[52:55]
	v_mfma_f32_16x16x32_bf16 v[52:55], v[152:155], v[184:187], v[52:55]
	v_mfma_f32_16x16x32_bf16 v[28:31], v[164:167], v[180:183], v[28:31]
	v_mfma_f32_16x16x32_bf16 v[28:31], v[168:171], v[184:187], v[28:31]
	v_mfma_f32_16x16x32_bf16 v[40:43], v[140:143], v[188:191], v[40:43]
	v_mfma_f32_16x16x32_bf16 v[40:43], v[144:147], v[192:195], v[40:43]
	v_mfma_f32_16x16x32_bf16 v[16:19], v[156:159], v[188:191], v[16:19]
	v_mfma_f32_16x16x32_bf16 v[16:19], v[160:163], v[192:195], v[16:19]
	v_mfma_f32_16x16x32_bf16 v[36:39], v[148:151], v[188:191], v[36:39]
	v_mfma_f32_16x16x32_bf16 v[36:39], v[152:155], v[192:195], v[36:39]
	v_mfma_f32_16x16x32_bf16 v[12:15], v[164:167], v[188:191], v[12:15]
	v_mfma_f32_16x16x32_bf16 v[12:15], v[168:171], v[192:195], v[12:15]
	v_mfma_f32_16x16x32_bf16 v[24:27], v[140:143], v[196:199], v[24:27]
	v_mfma_f32_16x16x32_bf16 v[24:27], v[144:147], v[200:203], v[24:27]
	v_mfma_f32_16x16x32_bf16 v[8:11], v[156:159], v[196:199], v[8:11]
	v_mfma_f32_16x16x32_bf16 v[8:11], v[160:163], v[200:203], v[8:11]
	v_mfma_f32_16x16x32_bf16 v[20:23], v[148:151], v[196:199], v[20:23]
	v_mfma_f32_16x16x32_bf16 v[20:23], v[152:155], v[200:203], v[20:23]
	v_mfma_f32_16x16x32_bf16 v[4:7], v[164:167], v[196:199], v[4:7]
	v_mfma_f32_16x16x32_bf16 v[4:7], v[168:171], v[200:203], v[4:7]
	s_setprio 0
	s_barrier
	s_add_i32 s47, s47, 2
	s_add_u32 s20, s20, 0x100
	s_addc_u32 s21, s21, 0
	s_add_u32 s45, s45, 0x100
	s_addc_u32 s46, s46, 0
	s_cmp_gt_u32 s47, 29

.LBB0_1009:
	s_ashr_i32 s13, s12, 31
	s_lshl_b64 s[14:15], s[12:13], 20
	s_add_u32 s14, s1, s14
	s_addc_u32 s15, s2, s15
	s_and_b64 s[16:17], s[38:39], exec
	s_cselect_b32 s13, s15, s23
	s_cselect_b32 s19, s14, s22
	s_ashr_i32 s11, s10, 31
	s_lshl_b64 s[16:17], s[10:11], 20
	s_add_u32 s16, s28, s16
	s_addc_u32 s17, s29, s17
	s_and_b64 s[26:27], s[38:39], exec
	s_cselect_b32 s11, s17, s25
	s_cselect_b32 s45, s16, s24
	s_add_u32 s22, s22, 0x80080
	s_addc_u32 s23, s23, 0
	s_add_u32 s46, s24, 0x100
	s_addc_u32 s47, s25, 0
	s_mov_b32 s48, -2
	s_sleep 2
	s_add_u32 s24, s22, 0xfff80080
	s_addc_u32 s25, s23, -1
	s_add_i32 s49, 0, 0x10000
	s_cmp_eq_u32 s48, 28
	s_cselect_b32 s27, s13, s25
	s_cselect_b32 s26, s19, s24
	s_cselect_b32 s25, s11, s47
	s_cselect_b32 s24, s45, s46
	s_add_i32 s52, 0, 0x14000
	v_add_u32_e32 v144, s49, v219
	v_add_u32_e32 v160, s52, v219
	ds_read_b128 v[116:119], v144
	ds_read_b128 v[124:127], v144 offset:1024
	ds_read_b128 v[132:135], v144 offset:2048
	ds_read_b128 v[144:147], v144 offset:3072
	ds_read_b128 v[148:151], v160
	ds_read_b128 v[152:155], v160 offset:1024
	ds_read_b128 v[156:159], v160 offset:2048
	ds_read_b128 v[160:163], v160 offset:3072
	v_lshl_add_u64 v[204:205], s[22:23], 0, v[192:193]
	s_add_i32 m0, s21, 0xc000
	ds_read_b128 v[164:167], v221
	ds_read_b128 v[168:171], v221 offset:1024
	ds_read_b128 v[172:175], v221 offset:2048
	ds_read_b128 v[176:179], v221 offset:3072
	ds_read_b128 v[180:183], v221 offset:4096
	ds_read_b128 v[184:187], v221 offset:5120
	ds_read_b128 v[196:199], v221 offset:6144
	ds_read_b128 v[200:203], v221 offset:7168
	global_load_lds_dwordx4 v[204:205], off
	v_lshl_add_u64 v[204:205], s[22:23], 0, v[194:195]
	s_add_i32 m0, s21, 0xe000
	s_nop 0
	global_load_lds_dwordx4 v[204:205], off
	s_waitcnt vmcnt(8)
	s_waitcnt lgkmcnt(0)
	s_barrier
	s_setprio 1
	s_waitcnt lgkmcnt(0)
	v_mfma_f32_16x16x32_bf16 v[140:143], v[116:119], v[164:167], 0
	v_mfma_f32_16x16x32_bf16 v[140:143], v[124:127], v[168:171], v[140:143]
	v_mfma_f32_16x16x32_bf16 v[128:131], v[148:151], v[164:167], 0
	v_mfma_f32_16x16x32_bf16 v[128:131], v[152:155], v[168:171], v[128:131]
	v_mfma_f32_16x16x32_bf16 v[136:139], v[132:135], v[164:167], 0
	v_mfma_f32_16x16x32_bf16 v[136:139], v[144:147], v[168:171], v[136:139]
	v_mfma_f32_16x16x32_bf16 v[120:123], v[156:159], v[164:167], 0
	v_mfma_f32_16x16x32_bf16 v[120:123], v[160:163], v[168:171], v[120:123]
	v_mfma_f32_16x16x32_bf16 v[112:115], v[116:119], v[172:175], 0
	v_mfma_f32_16x16x32_bf16 v[112:115], v[124:127], v[176:179], v[112:115]
	v_mfma_f32_16x16x32_bf16 v[104:107], v[148:151], v[172:175], 0
	v_mfma_f32_16x16x32_bf16 v[104:107], v[152:155], v[176:179], v[104:107]
	v_mfma_f32_16x16x32_bf16 v[108:111], v[132:135], v[172:175], 0
	v_mfma_f32_16x16x32_bf16 v[108:111], v[144:147], v[176:179], v[108:111]
	v_mfma_f32_16x16x32_bf16 v[100:103], v[156:159], v[172:175], 0
	v_mfma_f32_16x16x32_bf16 v[100:103], v[160:163], v[176:179], v[100:103]
	v_mfma_f32_16x16x32_bf16 v[96:99], v[116:119], v[180:183], 0
	v_mfma_f32_16x16x32_bf16 v[96:99], v[124:127], v[184:187], v[96:99]
	v_mfma_f32_16x16x32_bf16 v[88:91], v[148:151], v[180:183], 0
	v_mfma_f32_16x16x32_bf16 v[88:91], v[152:155], v[184:187], v[88:91]
	v_mfma_f32_16x16x32_bf16 v[92:95], v[132:135], v[180:183], 0
	v_mfma_f32_16x16x32_bf16 v[92:95], v[144:147], v[184:187], v[92:95]
	v_mfma_f32_16x16x32_bf16 v[84:87], v[156:159], v[180:183], 0
	v_mfma_f32_16x16x32_bf16 v[84:87], v[160:163], v[184:187], v[84:87]
	v_mfma_f32_16x16x32_bf16 v[80:83], v[116:119], v[196:199], 0
	v_mfma_f32_16x16x32_bf16 v[80:83], v[124:127], v[200:203], v[80:83]
	v_mfma_f32_16x16x32_bf16 v[72:75], v[148:151], v[196:199], 0
	v_mfma_f32_16x16x32_bf16 v[72:75], v[152:155], v[200:203], v[72:75]
	v_mfma_f32_16x16x32_bf16 v[76:79], v[132:135], v[196:199], 0
	v_mfma_f32_16x16x32_bf16 v[76:79], v[144:147], v[200:203], v[76:79]
	v_mfma_f32_16x16x32_bf16 v[68:71], v[156:159], v[196:199], 0
	v_mfma_f32_16x16x32_bf16 v[68:71], v[160:163], v[200:203], v[68:71]
	s_setprio 0
	s_barrier
	s_sleep 2
	s_add_i32 s49, s49, s30
	v_lshl_add_u64 v[204:205], s[24:25], 0, v[2:3]
	s_mov_b32 m0, s49
	ds_read_b128 v[164:167], v221 offset:16384
	ds_read_b128 v[168:171], v221 offset:17408
	ds_read_b128 v[172:175], v221 offset:18432
	ds_read_b128 v[176:179], v221 offset:19456
	ds_read_b128 v[180:183], v221 offset:20480
	ds_read_b128 v[184:187], v221 offset:21504
	ds_read_b128 v[196:199], v221 offset:22528
	ds_read_b128 v[200:203], v221 offset:23552
	global_load_lds_dwordx4 v[204:205], off
	s_add_i32 m0, s49, 0x2000
	s_add_u32 s50, s24, 0x80000
	v_lshl_add_u64 v[206:207], s[24:25], 0, v[190:191]
	s_addc_u32 s51, s25, 0
	s_add_i32 s49, s52, s30
	global_load_lds_dwordx4 v[206:207], off
	v_lshl_add_u64 v[208:209], s[50:51], 0, v[2:3]
	s_mov_b32 m0, s49
	v_lshl_add_u64 v[210:211], s[26:27], 0, v[188:189]
	global_load_lds_dwordx4 v[208:209], off
	v_lshl_add_u64 v[208:209], s[50:51], 0, v[190:191]
	s_add_i32 m0, s49, 0x2000
	s_nop 0
	global_load_lds_dwordx4 v[208:209], off
	v_lshl_add_u64 v[208:209], s[26:27], 0, v[0:1]
	s_mov_b32 m0, s21
	s_nop 0
	global_load_lds_dwordx4 v[208:209], off
	s_mov_b32 m0, s31
	s_nop 0
	global_load_lds_dwordx4 v[210:211], off
	s_waitcnt vmcnt(8)
	s_waitcnt lgkmcnt(0)
	s_barrier
	s_setprio 1
	s_waitcnt lgkmcnt(0)
	v_mfma_f32_16x16x32_bf16 v[64:67], v[116:119], v[164:167], 0
	v_mfma_f32_16x16x32_bf16 v[64:67], v[124:127], v[168:171], v[64:67]
	v_mfma_f32_16x16x32_bf16 v[56:59], v[148:151], v[164:167], 0
	v_mfma_f32_16x16x32_bf16 v[56:59], v[152:155], v[168:171], v[56:59]
	v_mfma_f32_16x16x32_bf16 v[60:63], v[132:135], v[164:167], 0
	v_mfma_f32_16x16x32_bf16 v[60:63], v[144:147], v[168:171], v[60:63]
	v_mfma_f32_16x16x32_bf16 v[52:55], v[156:159], v[164:167], 0
	v_mfma_f32_16x16x32_bf16 v[52:55], v[160:163], v[168:171], v[52:55]
	v_mfma_f32_16x16x32_bf16 v[48:51], v[116:119], v[172:175], 0
	v_mfma_f32_16x16x32_bf16 v[48:51], v[124:127], v[176:179], v[48:51]
	v_mfma_f32_16x16x32_bf16 v[40:43], v[148:151], v[172:175], 0
	v_mfma_f32_16x16x32_bf16 v[40:43], v[152:155], v[176:179], v[40:43]
	v_mfma_f32_16x16x32_bf16 v[44:47], v[132:135], v[172:175], 0
	v_mfma_f32_16x16x32_bf16 v[44:47], v[144:147], v[176:179], v[44:47]
	v_mfma_f32_16x16x32_bf16 v[36:39], v[156:159], v[172:175], 0
	v_mfma_f32_16x16x32_bf16 v[36:39], v[160:163], v[176:179], v[36:39]
	v_mfma_f32_16x16x32_bf16 v[32:35], v[116:119], v[180:183], 0
	v_mfma_f32_16x16x32_bf16 v[32:35], v[124:127], v[184:187], v[32:35]
	v_mfma_f32_16x16x32_bf16 v[24:27], v[148:151], v[180:183], 0
	v_mfma_f32_16x16x32_bf16 v[24:27], v[152:155], v[184:187], v[24:27]
	v_mfma_f32_16x16x32_bf16 v[28:31], v[132:135], v[180:183], 0
	v_mfma_f32_16x16x32_bf16 v[28:31], v[144:147], v[184:187], v[28:31]
	v_mfma_f32_16x16x32_bf16 v[20:23], v[156:159], v[180:183], 0
	v_mfma_f32_16x16x32_bf16 v[20:23], v[160:163], v[184:187], v[20:23]
	v_mfma_f32_16x16x32_bf16 v[16:19], v[116:119], v[196:199], 0
	v_mfma_f32_16x16x32_bf16 v[16:19], v[124:127], v[200:203], v[16:19]
	v_mfma_f32_16x16x32_bf16 v[8:11], v[148:151], v[196:199], 0
	v_mfma_f32_16x16x32_bf16 v[8:11], v[152:155], v[200:203], v[8:11]
	v_mfma_f32_16x16x32_bf16 v[12:15], v[132:135], v[196:199], 0
	v_mfma_f32_16x16x32_bf16 v[12:15], v[144:147], v[200:203], v[12:15]
	v_mfma_f32_16x16x32_bf16 v[4:7], v[156:159], v[196:199], 0
	v_mfma_f32_16x16x32_bf16 v[4:7], v[160:163], v[200:203], v[4:7]
	s_setprio 0
	s_barrier
	s_sleep 2
	s_add_i32 s49, 0, 0x18000
	s_add_i32 s50, 0, 0x1c000
	v_add_u32_e32 v144, s49, v219
	v_add_u32_e32 v160, s50, v219
	ds_read_b128 v[116:119], v144
	ds_read_b128 v[124:127], v144 offset:1024
	ds_read_b128 v[132:135], v144 offset:2048
	ds_read_b128 v[144:147], v144 offset:3072
	ds_read_b128 v[148:151], v160
	ds_read_b128 v[152:155], v160 offset:1024
	ds_read_b128 v[156:159], v160 offset:2048
	ds_read_b128 v[160:163], v160 offset:3072
	s_add_u32 s26, s26, 0x80000
	s_addc_u32 s27, s27, 0
	s_mov_b32 m0, s35
	v_lshl_add_u64 v[212:213], s[26:27], 0, v[0:1]
	ds_read_b128 v[164:167], v221 offset:32768
	ds_read_b128 v[168:171], v221 offset:33792
	ds_read_b128 v[172:175], v221 offset:34816
	ds_read_b128 v[176:179], v221 offset:35840
	ds_read_b128 v[180:183], v221 offset:36864
	ds_read_b128 v[184:187], v221 offset:37888
	ds_read_b128 v[196:199], v221 offset:38912
	ds_read_b128 v[200:203], v221 offset:39936
	global_load_lds_dwordx4 v[212:213], off
	v_lshl_add_u64 v[212:213], s[26:27], 0, v[188:189]
	s_mov_b32 m0, s40
	s_nop 0
	global_load_lds_dwordx4 v[212:213], off
	s_waitcnt vmcnt(8)
	s_waitcnt lgkmcnt(0)
	s_barrier
	s_setprio 1
	s_waitcnt lgkmcnt(0)
	v_mfma_f32_16x16x32_bf16 v[140:143], v[116:119], v[164:167], v[140:143]
	v_mfma_f32_16x16x32_bf16 v[140:143], v[124:127], v[168:171], v[140:143]
	v_mfma_f32_16x16x32_bf16 v[128:131], v[148:151], v[164:167], v[128:131]
	v_mfma_f32_16x16x32_bf16 v[128:131], v[152:155], v[168:171], v[128:131]
	v_mfma_f32_16x16x32_bf16 v[136:139], v[132:135], v[164:167], v[136:139]
	v_mfma_f32_16x16x32_bf16 v[136:139], v[144:147], v[168:171], v[136:139]
	v_mfma_f32_16x16x32_bf16 v[120:123], v[156:159], v[164:167], v[120:123]
	v_mfma_f32_16x16x32_bf16 v[120:123], v[160:163], v[168:171], v[120:123]
	v_mfma_f32_16x16x32_bf16 v[112:115], v[116:119], v[172:175], v[112:115]
	v_mfma_f32_16x16x32_bf16 v[112:115], v[124:127], v[176:179], v[112:115]
	v_mfma_f32_16x16x32_bf16 v[104:107], v[148:151], v[172:175], v[104:107]
	v_mfma_f32_16x16x32_bf16 v[104:107], v[152:155], v[176:179], v[104:107]
	v_mfma_f32_16x16x32_bf16 v[108:111], v[132:135], v[172:175], v[108:111]
	v_mfma_f32_16x16x32_bf16 v[108:111], v[144:147], v[176:179], v[108:111]
	v_mfma_f32_16x16x32_bf16 v[100:103], v[156:159], v[172:175], v[100:103]
	v_mfma_f32_16x16x32_bf16 v[100:103], v[160:163], v[176:179], v[100:103]
	v_mfma_f32_16x16x32_bf16 v[96:99], v[116:119], v[180:183], v[96:99]
	v_mfma_f32_16x16x32_bf16 v[96:99], v[124:127], v[184:187], v[96:99]
	v_mfma_f32_16x16x32_bf16 v[88:91], v[148:151], v[180:183], v[88:91]
	v_mfma_f32_16x16x32_bf16 v[88:91], v[152:155], v[184:187], v[88:91]
	v_mfma_f32_16x16x32_bf16 v[92:95], v[132:135], v[180:183], v[92:95]
	v_mfma_f32_16x16x32_bf16 v[92:95], v[144:147], v[184:187], v[92:95]
	v_mfma_f32_16x16x32_bf16 v[84:87], v[156:159], v[180:183], v[84:87]
	v_mfma_f32_16x16x32_bf16 v[84:87], v[160:163], v[184:187], v[84:87]
	v_mfma_f32_16x16x32_bf16 v[80:83], v[116:119], v[196:199], v[80:83]
	v_mfma_f32_16x16x32_bf16 v[80:83], v[124:127], v[200:203], v[80:83]
	v_mfma_f32_16x16x32_bf16 v[72:75], v[148:151], v[196:199], v[72:75]
	v_mfma_f32_16x16x32_bf16 v[72:75], v[152:155], v[200:203], v[72:75]
	v_mfma_f32_16x16x32_bf16 v[76:79], v[132:135], v[196:199], v[76:79]
	v_mfma_f32_16x16x32_bf16 v[76:79], v[144:147], v[200:203], v[76:79]
	v_mfma_f32_16x16x32_bf16 v[68:71], v[156:159], v[196:199], v[68:71]
	v_mfma_f32_16x16x32_bf16 v[68:71], v[160:163], v[200:203], v[68:71]
	s_setprio 0
	s_barrier
	s_sleep 2
	s_add_i32 s26, s49, s30
	v_lshl_add_u64 v[204:205], v[204:205], 0, s[66:67]
	s_mov_b32 m0, s26
	ds_read_b128 v[164:167], v221 offset:49152
	ds_read_b128 v[168:171], v221 offset:50176
	ds_read_b128 v[172:175], v221 offset:51200
	ds_read_b128 v[176:179], v221 offset:52224
	ds_read_b128 v[180:183], v221 offset:53248
	ds_read_b128 v[184:187], v221 offset:54272
	ds_read_b128 v[196:199], v221 offset:55296
	ds_read_b128 v[200:203], v221 offset:56320
	global_load_lds_dwordx4 v[204:205], off
	s_add_i32 m0, s26, 0x2000
	s_add_u32 s24, s24, 0x80080
	v_lshl_add_u64 v[204:205], v[206:207], 0, s[66:67]
	s_addc_u32 s25, s25, 0
	s_add_i32 s26, s50, s30
	global_load_lds_dwordx4 v[204:205], off
	v_lshl_add_u64 v[204:205], s[24:25], 0, v[2:3]
	s_mov_b32 m0, s26
	s_nop 0
	global_load_lds_dwordx4 v[204:205], off
	v_lshl_add_u64 v[204:205], s[24:25], 0, v[190:191]
	s_add_i32 m0, s26, 0x2000
	s_nop 0
	global_load_lds_dwordx4 v[204:205], off
	v_lshl_add_u64 v[204:205], v[208:209], 0, s[66:67]
	s_mov_b32 m0, s41
	s_nop 0
	global_load_lds_dwordx4 v[204:205], off
	v_lshl_add_u64 v[204:205], v[210:211], 0, s[66:67]
	s_mov_b32 m0, s42
	s_nop 0
	global_load_lds_dwordx4 v[204:205], off
	s_waitcnt vmcnt(8)
	s_waitcnt lgkmcnt(0)
	s_barrier
	s_setprio 1
	s_waitcnt lgkmcnt(0)
	v_mfma_f32_16x16x32_bf16 v[64:67], v[116:119], v[164:167], v[64:67]
	v_mfma_f32_16x16x32_bf16 v[64:67], v[124:127], v[168:171], v[64:67]
	v_mfma_f32_16x16x32_bf16 v[56:59], v[148:151], v[164:167], v[56:59]
	v_mfma_f32_16x16x32_bf16 v[56:59], v[152:155], v[168:171], v[56:59]
	v_mfma_f32_16x16x32_bf16 v[60:63], v[132:135], v[164:167], v[60:63]
	v_mfma_f32_16x16x32_bf16 v[60:63], v[144:147], v[168:171], v[60:63]
	v_mfma_f32_16x16x32_bf16 v[52:55], v[156:159], v[164:167], v[52:55]
	v_mfma_f32_16x16x32_bf16 v[52:55], v[160:163], v[168:171], v[52:55]
	v_mfma_f32_16x16x32_bf16 v[48:51], v[116:119], v[172:175], v[48:51]
	v_mfma_f32_16x16x32_bf16 v[48:51], v[124:127], v[176:179], v[48:51]
	v_mfma_f32_16x16x32_bf16 v[40:43], v[148:151], v[172:175], v[40:43]
	v_mfma_f32_16x16x32_bf16 v[40:43], v[152:155], v[176:179], v[40:43]
	v_mfma_f32_16x16x32_bf16 v[44:47], v[132:135], v[172:175], v[44:47]
	v_mfma_f32_16x16x32_bf16 v[44:47], v[144:147], v[176:179], v[44:47]
	v_mfma_f32_16x16x32_bf16 v[36:39], v[156:159], v[172:175], v[36:39]
	v_mfma_f32_16x16x32_bf16 v[36:39], v[160:163], v[176:179], v[36:39]
	v_mfma_f32_16x16x32_bf16 v[32:35], v[116:119], v[180:183], v[32:35]
	v_mfma_f32_16x16x32_bf16 v[32:35], v[124:127], v[184:187], v[32:35]
	v_mfma_f32_16x16x32_bf16 v[24:27], v[148:151], v[180:183], v[24:27]
	v_mfma_f32_16x16x32_bf16 v[24:27], v[152:155], v[184:187], v[24:27]
	v_mfma_f32_16x16x32_bf16 v[28:31], v[132:135], v[180:183], v[28:31]
	v_mfma_f32_16x16x32_bf16 v[28:31], v[144:147], v[184:187], v[28:31]
	v_mfma_f32_16x16x32_bf16 v[20:23], v[156:159], v[180:183], v[20:23]
	v_mfma_f32_16x16x32_bf16 v[20:23], v[160:163], v[184:187], v[20:23]
	v_mfma_f32_16x16x32_bf16 v[16:19], v[116:119], v[196:199], v[16:19]
	v_mfma_f32_16x16x32_bf16 v[16:19], v[124:127], v[200:203], v[16:19]
	v_mfma_f32_16x16x32_bf16 v[8:11], v[148:151], v[196:199], v[8:11]
	v_mfma_f32_16x16x32_bf16 v[8:11], v[152:155], v[200:203], v[8:11]
	v_mfma_f32_16x16x32_bf16 v[12:15], v[132:135], v[196:199], v[12:15]
	v_mfma_f32_16x16x32_bf16 v[12:15], v[144:147], v[200:203], v[12:15]
	v_mfma_f32_16x16x32_bf16 v[4:7], v[156:159], v[196:199], v[4:7]
	v_mfma_f32_16x16x32_bf16 v[4:7], v[160:163], v[200:203], v[4:7]
	s_setprio 0
	s_barrier
	s_add_i32 s48, s48, 2
	s_add_u32 s22, s22, 0x100
	s_addc_u32 s23, s23, 0
	s_add_u32 s46, s46, 0x100
	s_addc_u32 s47, s47, 0
	s_cmp_gt_u32 s48, 29
